# static s_setprio 1 for blocks >= 256 (second co-resident block per CU) during the GEMM phases, reset at every phase boundary
# baseline (speedup 1.0000x reference)
.LBB0_141:
	s_or_b64 exec, exec, s[0:1]
	s_setprio 0
	s_and_b32 s0, s28, 7
	s_cmp_lg_u32 s0, 0
	s_cselect_b64 s[4:5], -1, 0
	v_mov_b32_e32 v98, v174
	s_waitcnt lgkmcnt(0)
	v_mov_b32_e32 v0, v174
	v_writelane_b32 v254, s4, 56
	s_barrier
	s_nop 0
	v_writelane_b32 v254, s5, 57
	v_ashrrev_i32_e32 v99, 7, v0
	s_cmp_eq_u32 s0, 0
	v_bfe_u32 v100, v0, 6, 1
	s_cbranch_scc1 .LBB0_150
	s_cmpk_gt_i32 s2, 0xfef
	s_cbranch_scc1 .LBB0_149
	v_and_b32_e32 v0, 15, v98
	v_lshl_or_b32 v101, v99, 6, v0
	v_lshrrev_b32_e32 v0, 2, v98
	v_and_b32_e32 v0, 12, v0
	v_lshl_or_b32 v102, v100, 6, v0
	v_mov_b32_e32 v65, 0
	s_mov_b64 s[0:1], 0x80
	s_mov_b64 s[4:5], 0x100
	s_movk_i32 s3, 0x1e20
	s_mov_b32 s86, s2
	s_branch .LBB0_145

.LBB0_150:
.LBB0_151:
	s_ashr_i32 s3, s2, 3
	s_cmpk_gt_i32 s3, 0x1fd
	s_cbranch_scc1 .LBB0_158
	v_and_b32_e32 v0, 15, v98
	v_lshl_or_b32 v99, v99, 6, v0
	v_lshrrev_b32_e32 v0, 2, v98
	s_and_b32 s84, s2, 7
	v_and_b32_e32 v0, 12, v0
	s_lshl_b32 s0, s3, 3
	s_ashr_i32 s85, s28, 3
	v_lshl_or_b32 v98, v100, 6, v0
	s_or_b32 s86, s0, s84
	v_mov_b32_e32 v65, 0
	s_mov_b64 s[0:1], 0x80
	s_mov_b64 s[4:5], 0x100
	s_movk_i32 s87, 0x1e20
	s_cmp_lt_u32 s2, 0x100
	s_cbranch_scc1 .Lgprio_0
	s_setprio 1
.Lgprio_0:
	s_branch .LBB0_154
.LBB0_153:
	v_lshl_add_u32 v64, s8, 7, v99
	v_lshl_or_b32 v66, s6, 7, v98
	v_cvt_pk_f16_f32 v63, v62, v63
	v_cvt_pk_f16_f32 v62, v60, v61
	v_mov_b64_e32 v[60:61], s[42:43]
	v_ashrrev_i32_e32 v67, 31, v66
	v_cvt_pk_f16_f32 v51, v50, v51
	v_cvt_pk_f16_f32 v50, v48, v49
	v_or_b32_e32 v48, 16, v64
	v_cvt_pk_f16_f32 v35, v34, v35
	v_cvt_pk_f16_f32 v34, v32, v33
	v_or_b32_e32 v32, 32, v64
	v_cvt_pk_f16_f32 v19, v18, v19
	v_cvt_pk_f16_f32 v18, v16, v17
	v_or_b32_e32 v16, 48, v64
	v_mad_i64_i32 v[68:69], s[6:7], v64, s87, v[60:61]
	v_lshlrev_b64 v[66:67], 1, v[66:67]
	v_cvt_pk_f16_f32 v47, v46, v47
	v_cvt_pk_f16_f32 v46, v44, v45
	v_mad_i64_i32 v[44:45], s[6:7], v48, s87, v[60:61]
	v_cvt_pk_f16_f32 v31, v30, v31
	v_cvt_pk_f16_f32 v30, v28, v29
	v_mad_i64_i32 v[28:29], s[6:7], v32, s87, v[60:61]
	v_cvt_pk_f16_f32 v15, v14, v15
	v_cvt_pk_f16_f32 v14, v12, v13
	v_mad_i64_i32 v[12:13], s[6:7], v16, s87, v[60:61]
	s_add_i32 s3, s3, s85
	s_add_i32 s86, s86, s28
	v_lshl_add_u64 v[68:69], v[68:69], 0, v[66:67]
	v_cvt_pk_f16_f32 v59, v58, v59
	v_cvt_pk_f16_f32 v58, v56, v57
	v_cvt_pk_f16_f32 v55, v54, v55
	v_cvt_pk_f16_f32 v54, v52, v53
	v_lshl_add_u64 v[44:45], v[44:45], 0, v[66:67]
	v_cvt_pk_f16_f32 v43, v42, v43
	v_cvt_pk_f16_f32 v42, v40, v41
	v_cvt_pk_f16_f32 v39, v38, v39
	v_cvt_pk_f16_f32 v38, v36, v37
	v_lshl_add_u64 v[28:29], v[28:29], 0, v[66:67]
	v_cvt_pk_f16_f32 v27, v26, v27
	v_cvt_pk_f16_f32 v26, v24, v25
	v_cvt_pk_f16_f32 v23, v22, v23
	v_cvt_pk_f16_f32 v22, v20, v21
	v_lshl_add_u64 v[12:13], v[12:13], 0, v[66:67]
	v_cvt_pk_f16_f32 v11, v10, v11
	v_cvt_pk_f16_f32 v10, v8, v9
	v_cvt_pk_f16_f32 v7, v6, v7
	v_cvt_pk_f16_f32 v6, v4, v5
	v_cvt_pk_f16_f32 v3, v2, v3
	v_cvt_pk_f16_f32 v2, v0, v1
	s_cmpk_gt_i32 s3, 0x1fd
	s_waitcnt vmcnt(0)
	s_barrier
	global_store_dwordx2 v[68:69], v[62:63], off
	global_store_dwordx2 v[68:69], v[58:59], off offset:32
	global_store_dwordx2 v[68:69], v[54:55], off offset:64
	global_store_dwordx2 v[68:69], v[50:51], off offset:96
	global_store_dwordx2 v[44:45], v[46:47], off
	global_store_dwordx2 v[44:45], v[42:43], off offset:32
	global_store_dwordx2 v[44:45], v[38:39], off offset:64
	global_store_dwordx2 v[44:45], v[34:35], off offset:96
	global_store_dwordx2 v[28:29], v[30:31], off
	global_store_dwordx2 v[28:29], v[26:27], off offset:32
	global_store_dwordx2 v[28:29], v[22:23], off offset:64
	global_store_dwordx2 v[28:29], v[18:19], off offset:96
	global_store_dwordx2 v[12:13], v[14:15], off
	global_store_dwordx2 v[12:13], v[10:11], off offset:32
	global_store_dwordx2 v[12:13], v[6:7], off offset:64
	global_store_dwordx2 v[12:13], v[2:3], off offset:96
	s_cbranch_scc1 .LBB0_158

.LBB0_210:
	s_or_b64 exec, exec, s[0:1]
	s_setprio 0
	s_waitcnt lgkmcnt(0)
	v_mov_b32_e32 v0, v174
	s_barrier
	s_mov_b32 s0, 0x10100
	v_add_u32_e32 v1, s30, v0
	v_cmp_gt_i32_e32 vcc, s0, v1
	s_and_saveexec_b64 s[4:5], vcc
	s_cbranch_execz .LBB0_213
	v_and_b32_e32 v2, 31, v0
	v_cvt_f32_ubyte0_e32 v3, v2
	v_mul_f32_e32 v3, 0xbd000000, v3
	v_mov_b32_e32 v4, 0x461c4000
	v_cmp_eq_f32_e32 vcc, 0, v3
	s_mov_b32 s0, 0x3f2aaaab
	s_movk_i32 s6, 0x204
	v_cndmask_b32_e64 v14, v4, 1.0, vcc
	v_frexp_mant_f32_e32 v4, v14
	v_cmp_gt_f32_e64 s[0:1], s0, v4
	s_mov_b32 s8, 0x42b17218
	s_mov_b32 s7, 0x7f800000
	v_cndmask_b32_e64 v5, 1.0, 2.0, s[0:1]
	v_mul_f32_e32 v4, v4, v5
	v_add_f32_e32 v7, 1.0, v4
	v_rcp_f32_e32 v12, v7
	v_add_f32_e32 v5, -1.0, v7
	v_sub_f32_e32 v9, v4, v5
	v_add_f32_e32 v5, -1.0, v4
	v_mul_f32_e32 v13, v5, v12
	v_mul_f32_e32 v6, v7, v13
	v_fma_f32 v8, v13, v7, -v6
	v_fmac_f32_e32 v8, v13, v9
	v_add_f32_e32 v4, v6, v8
	v_sub_f32_e32 v7, v5, v4
	v_pk_add_f32 v[10:11], v[4:5], v[6:7] neg_lo:[0,1] neg_hi:[0,1]
	v_mov_b32_e32 v9, v4
	v_pk_add_f32 v[4:5], v[10:11], v[8:9] neg_lo:[0,1] neg_hi:[0,1]
	v_mov_b32_e32 v8, 0x3e91f4c4
	v_add_f32_e32 v4, v4, v5
	v_add_f32_e32 v4, v7, v4
	v_mul_f32_e32 v5, v12, v4
	v_add_f32_e32 v4, v13, v5
	v_sub_f32_e32 v6, v4, v13
	v_sub_f32_e32 v15, v5, v6
	v_mul_f32_e32 v5, v4, v4
	v_fma_f32 v7, v4, v4, -v5
	v_add_f32_e32 v6, v15, v15
	v_fmac_f32_e32 v7, v4, v6
	v_add_f32_e32 v6, v5, v7
	v_fmac_f32_e32 v8, 0x3e76c4e1, v6
	v_fmaak_f32 v8, v6, v8, 0x3ecccdef
	v_sub_f32_e32 v5, v6, v5
	v_sub_f32_e32 v16, v7, v5
	v_mul_f32_e32 v5, v6, v8
	v_fma_f32 v7, v6, v8, -v5
	v_fmac_f32_e32 v7, v16, v8
	v_add_f32_e32 v8, v5, v7
	v_add_f32_e32 v9, 0x3f2aaaaa, v8
	v_sub_f32_e32 v5, v8, v5
	v_sub_f32_e32 v5, v7, v5
	v_add_f32_e32 v7, 0xbf2aaaaa, v9
	v_add_f32_e32 v5, 0x31739010, v5
	v_sub_f32_e32 v7, v8, v7
	v_pk_mul_f32 v[10:11], v[4:5], v[6:7]
	v_pk_add_f32 v[12:13], v[4:5], v[6:7]
	v_fma_f32 v8, v6, v4, -v10
	v_fmac_f32_e32 v8, v6, v15
	v_mov_b32_e32 v11, v13
	v_fmac_f32_e32 v8, v16, v4
	v_pk_add_f32 v[6:7], v[10:11], v[8:9]
	v_ldexp_f32 v16, v15, 1
	v_sub_f32_e32 v5, v6, v10
	v_sub_f32_e32 v5, v8, v5
	v_sub_f32_e32 v8, v9, v7
	v_add_f32_e32 v11, v13, v8
	v_pk_mul_f32 v[8:9], v[6:7], v[6:7] op_sel:[0,1] op_sel_hi:[1,0]
	v_cvt_f64_f32_e32 v[12:13], v14
	v_frexp_exp_i32_f64_e32 v9, v[12:13]
	v_subbrev_co_u32_e64 v9, s[0:1], 0, v9, s[0:1]
	v_cvt_f32_i32_e32 v9, v9
	v_fma_f32 v10, v6, v7, -v8
	v_fmac_f32_e32 v10, v6, v11
	s_mov_b32 s0, 0x3f317218
	v_mul_f32_e32 v6, 0x3f317218, v9
	v_fmac_f32_e32 v10, v5, v7
	v_fma_f32 v5, v9, s0, -v6
	v_fmamk_f32 v12, v9, 0xb102e308, v5
	v_ldexp_f32 v13, v4, 1
	v_add_f32_e32 v7, v8, v10
	v_pk_add_f32 v[4:5], v[6:7], v[12:13]
	v_mov_b32_e32 v14, v7
	v_mov_b32_e32 v15, v5
	v_mov_b32_e32 v9, v13
	v_pk_add_f32 v[8:9], v[14:15], v[8:9] neg_lo:[0,1] neg_hi:[0,1]
	v_mov_b32_e32 v11, v7
	v_pk_add_f32 v[8:9], v[10:11], v[8:9] neg_lo:[0,1] neg_hi:[0,1]
	v_mov_b32_e32 v13, v4
	v_add_f32_e32 v7, v16, v8
	v_add_f32_e32 v7, v7, v9
	v_pk_add_f32 v[8:9], v[4:5], v[6:7] neg_lo:[0,1] neg_hi:[0,1]
	v_pk_add_f32 v[10:11], v[4:5], v[6:7]
	v_mov_b32_e32 v6, v7
	v_mov_b32_e32 v9, v11
	v_pk_add_f32 v[14:15], v[12:13], v[8:9] neg_lo:[0,1] neg_hi:[0,1]
	v_pk_add_f32 v[8:9], v[12:13], v[8:9]
	v_mov_b32_e32 v7, v4
	v_pk_add_f32 v[12:13], v[8:9], v[4:5] op_sel:[1,0] op_sel_hi:[0,1] neg_lo:[0,1] neg_hi:[0,1]
	v_pk_add_f32 v[16:17], v[10:11], v[12:13] op_sel_hi:[1,0] neg_lo:[0,1] neg_hi:[0,1]
	v_mov_b32_e32 v10, v11
	v_mov_b32_e32 v11, v9
	v_pk_mov_b32 v[12:13], v[4:5], v[12:13] op_sel:[1,0]
	v_mov_b32_e32 v16, v14
	v_pk_add_f32 v[10:11], v[10:11], v[12:13] neg_lo:[0,1] neg_hi:[0,1]
	v_mov_b32_e32 v15, v9
	v_pk_add_f32 v[4:5], v[6:7], v[10:11] neg_lo:[0,1] neg_hi:[0,1]
	s_lshl_b32 s3, s28, 8
	v_pk_add_f32 v[6:7], v[16:17], v[4:5]
	s_nop 0
	v_pk_add_f32 v[10:11], v[6:7], v[6:7] op_sel:[0,1] op_sel_hi:[1,0]
	s_nop 0
	v_pk_add_f32 v[8:9], v[8:9], v[10:11] op_sel:[1,0] op_sel_hi:[0,1]
	v_mov_b32_e32 v7, v8
	v_pk_add_f32 v[12:13], v[6:7], v[14:15] neg_lo:[0,1] neg_hi:[0,1]
	v_mov_b32_e32 v5, v10
	v_sub_f32_e32 v6, v6, v12
	v_pk_add_f32 v[4:5], v[4:5], v[12:13] neg_lo:[0,1] neg_hi:[0,1]
	v_sub_f32_e32 v6, v14, v6
	v_add_f32_e32 v4, v4, v6
	v_add_f32_e32 v4, v4, v5
	v_add_f32_e32 v5, v8, v4
	v_sub_f32_e32 v6, v5, v8
	v_sub_f32_e32 v4, v4, v6
	v_mul_f32_e32 v6, v3, v5
	v_fma_f32 v5, v3, v5, -v6
	v_fmac_f32_e32 v5, v3, v4
	v_add_f32_e32 v4, v6, v5
	v_cmp_class_f32_e64 s[0:1], v6, s6
	v_sub_f32_e32 v7, v4, v6
	v_sub_f32_e32 v5, v5, v7
	v_cndmask_b32_e64 v4, v4, v6, s[0:1]
	v_mov_b32_e32 v6, 0x37000000
	v_cmp_eq_f32_e64 s[0:1], s8, v4
	s_nop 1
	v_cndmask_b32_e64 v6, 0, v6, s[0:1]
	v_sub_f32_e32 v7, v4, v6
	s_mov_b32 s0, 0x3fb8aa3b
	v_mul_f32_e32 v8, 0x3fb8aa3b, v7
	v_fma_f32 v9, v7, s0, -v8
	v_rndne_f32_e32 v10, v8
	v_fmamk_f32 v9, v7, 0x32a5705f, v9
	v_sub_f32_e32 v8, v8, v10
	v_add_f32_e32 v8, v8, v9
	v_exp_f32_e32 v8, v8
	v_cvt_i32_f32_e32 v9, v10
	v_cmp_neq_f32_e64 s[0:1], |v4|, s7
	s_nop 1
	v_cndmask_b32_e64 v4, 0, v5, s[0:1]
	s_mov_b32 s0, 0xc2ce8ed0
	v_ldexp_f32 v5, v8, v9
	v_cmp_ngt_f32_e64 s[0:1], s0, v7
	v_add_f32_e32 v4, v6, v4
	v_mov_b32_e32 v6, 0x7f800000
	v_cndmask_b32_e64 v5, 0, v5, s[0:1]
	v_cmp_nlt_f32_e64 s[0:1], s8, v7
	s_nop 1
	v_cndmask_b32_e64 v5, v6, v5, s[0:1]
	v_fma_f32 v4, v5, v4, v5
	v_cmp_class_f32_e64 s[0:1], v5, s6
	s_nop 1
	v_cndmask_b32_e64 v4, v4, v5, s[0:1]
	v_cmp_neq_f32_e64 s[0:1], v3, |v3|
	s_nop 1
	v_cndmask_b32_e64 v5, v6, 0, s[0:1]
	v_cndmask_b32_e64 v5, v5, 1.0, vcc
	v_cmp_class_f32_e64 s[0:1], v3, s6
	s_mov_b32 s6, 0x6dc9c883
	s_mov_b32 s7, 0x3fc45f30
	v_cndmask_b32_e64 v3, |v4|, v5, s[0:1]
	s_mov_b64 s[0:1], 0

.LBB0_285:
	s_or_b64 exec, exec, s[0:1]
	s_setprio 0
	v_readlane_b32 s4, v254, 3
	v_readlane_b32 s18, v254, 17
	v_readlane_b32 s19, v254, 18
	s_add_u32 s0, s18, 0x5790000
	v_readlane_b32 s5, v254, 4
	v_readlane_b32 s6, v254, 5
	v_readlane_b32 s7, v254, 6
	v_readlane_b32 s8, v254, 7
	v_readlane_b32 s9, v254, 8
	v_readlane_b32 s10, v254, 9
	v_readlane_b32 s11, v254, 10
	v_readlane_b32 s12, v254, 11
	v_readlane_b32 s13, v254, 12
	v_readlane_b32 s14, v254, 13
	v_readlane_b32 s15, v254, 14
	v_readlane_b32 s16, v254, 15
	v_readlane_b32 s17, v254, 16
	v_writelane_b32 v254, s0, 62
	s_addc_u32 s0, s19, 0
	s_add_u32 s26, s74, 0x1000
	s_addc_u32 s27, s75, 0
	v_writelane_b32 v254, s0, 63
	s_add_u32 s0, s74, 0x1200
	s_addc_u32 s1, s75, 0
	s_mov_b32 s87, 0
	v_writelane_b32 v255, s0, 0
	v_mov_b32_e32 v28, 0
	s_movk_i32 s7, 0x1e20
	v_writelane_b32 v255, s1, 1
	s_add_u32 s0, s74, 0x1400
	s_addc_u32 s1, s75, 0
	v_writelane_b32 v255, s0, 2
	s_movk_i32 s24, 0x1000
	s_mov_b32 s90, 0xbfb8aa3b
	v_writelane_b32 v255, s1, 3
	s_add_u32 s0, s74, 0x1600
	s_addc_u32 s1, s75, 0
	v_writelane_b32 v255, s0, 4
	s_mov_b32 s91, 0x800000
	s_mov_b32 s92, 0x3f317217
	v_writelane_b32 v255, s1, 5
	s_add_u32 s0, s74, 0x1800
	s_addc_u32 s1, s75, 0
	v_writelane_b32 v255, s0, 6
	s_mov_b32 s93, 0x7f800000
	s_mov_b32 s6, 0x3e3504f3
	v_writelane_b32 v255, s1, 7
	s_add_u32 s0, s74, 0x1a00
	s_addc_u32 s1, s75, 0
	v_writelane_b32 v255, s0, 8
	s_movk_i32 s94, 0x800
	v_mov_b32_e32 v71, 0x42800000
	v_writelane_b32 v255, s1, 9
	s_add_u32 s0, s74, 0x1c00
	s_addc_u32 s1, s75, 0
	v_writelane_b32 v255, s0, 10
	v_mov_b32_e32 v72, 0x1800
	v_mov_b32_e32 v73, 0x1600
	v_writelane_b32 v255, s1, 11
	s_add_u32 s0, s74, 0x1e00
	s_addc_u32 s1, s75, 0
	v_writelane_b32 v255, s0, 12
	v_mov_b32_e32 v74, 0x3e000000
	v_mov_b32_e32 v75, 0x41b17218
	v_writelane_b32 v255, s1, 13
	s_add_u32 s0, s18, 0x4790000
	v_writelane_b32 v255, s0, 14
	s_addc_u32 s0, s19, 0
	v_writelane_b32 v255, s0, 15
	s_add_u32 s0, s18, 0x7090000
	v_writelane_b32 v255, s0, 16
	s_addc_u32 s0, s19, 0
	v_writelane_b32 v255, s0, 17
	s_add_u32 s0, s18, 0x5f90000
	v_writelane_b32 v255, s0, 18
	s_addc_u32 s0, s19, 0
	s_add_u32 s31, s18, 0x4690000
	v_writelane_b32 v255, s0, 19
	s_addc_u32 s0, s19, 0
	v_writelane_b32 v255, s0, 20
	s_add_u32 s0, s18, 0x4500000
	v_writelane_b32 v255, s0, 22
	s_addc_u32 s0, s19, 0
	v_writelane_b32 v255, s0, 24
	s_add_u32 s0, s18, 0x4400000
	v_writelane_b32 v255, s0, 26
	s_addc_u32 s0, s19, 0
	v_writelane_b32 v255, s0, 42
	s_add_i32 s3, 0, 0x10010
	s_add_i32 s0, 0, 0x3000
	v_writelane_b32 v255, s0, 44
	v_mov_b32_e32 v70, s3
	v_mov_b32_e32 v76, 0xc00
	v_mov_b32_e32 v77, 0xb00
	v_mov_b32_e32 v78, 0x1000
	s_waitcnt lgkmcnt(0)
	s_barrier
	s_mov_b32 s99, -1
	s_mov_b32 s100, 0
	s_cmp_lg_u32 s28, 0x200
	s_cbranch_scc1 .Lmap_done_0
	s_movk_i32 s100, 0x140
	s_cmp_ge_u32 s2, 0x100
	s_cbranch_scc1 .Lmap_hi_0
	s_mov_b32 s99, s2
	s_cmp_lt_u32 s2, 192
	s_cbranch_scc1 .Lmap_done_0
	s_add_u32 s99, s2, 64
	s_branch .Lmap_done_0

.LBB0_527:
	v_writelane_b32 v255, s30, 42
	s_or_b64 exec, exec, s[0:1]
	s_setprio 0
	v_readlane_b32 s0, v254, 60
	v_readlane_b32 s1, v254, 61
	s_waitcnt lgkmcnt(0)
	v_mov_b32_e32 v0, v174
	s_andn2_b64 vcc, exec, s[0:1]
	v_cndmask_b32_e64 v1, 0, 1, s[0:1]
	v_cmp_ne_u32_e64 s[30:31], 1, v1
	s_barrier
	s_cbranch_vccnz .LBB0_543
	v_and_b32_e32 v1, 63, v0
	v_lshlrev_b32_e32 v1, 2, v1
	global_load_dword v17, v1, s[72:73]
	global_load_dword v70, v1, s[78:79]
	v_ashrrev_i32_e32 v1, 31, v0
	v_readlane_b32 s52, v254, 21
	v_lshlrev_b64 v[2:3], 2, v[0:1]
	v_readlane_b32 s66, v254, 35
	v_readlane_b32 s67, v254, 36
	v_readlane_b32 s4, v254, 3
	v_readlane_b32 s5, v254, 4
	s_waitcnt vmcnt(7)
	v_lshl_add_u64 v[4:5], s[66:67], 0, v[2:3]
	v_readlane_b32 s64, v254, 33
	v_readlane_b32 s65, v254, 34
	global_load_dword v71, v[4:5], off
	v_lshl_add_u64 v[4:5], s[4:5], 0, v[2:3]
	v_readlane_b32 s62, v254, 31
	v_readlane_b32 s63, v254, 32
	global_load_dword v72, v[4:5], off
	v_lshl_add_u64 v[4:5], s[64:65], 0, v[2:3]
	global_load_dword v73, v[4:5], off
	v_lshl_add_u64 v[4:5], s[62:63], 0, v[2:3]
	global_load_dword v74, v[4:5], off
	v_lshl_add_u64 v[4:5], s[80:81], 0, v[2:3]
	global_load_dword v75, v[4:5], off
	global_load_dword v76, v[4:5], off offset:1280
	global_load_dword v77, v[4:5], off offset:2304
	v_lshlrev_b32_e32 v4, 3, v0
	v_ashrrev_i32_e32 v78, 4, v0
	v_and_b32_e32 v16, 0x78, v4
	s_movk_i32 s0, 0x110
	v_mul_lo_u32 v4, v78, s0
	v_lshlrev_b32_e32 v5, 1, v16
	v_add3_u32 v80, 0, v4, v5
	v_and_b32_e32 v5, 15, v0
	v_mul_u32_u24_e32 v6, 0x110, v5
	v_and_b32_e32 v4, 48, v0
	v_add3_u32 v81, 0, v6, v4
	v_lshlrev_b32_e32 v6, 8, v0
	v_and_b32_e32 v6, 0x3000, v6
	v_add_u32_e32 v9, 0, v6
	v_mbcnt_hi_u32_b32 v6, -1, v175
	v_and_b32_e32 v10, 64, v6
	v_xor_b32_e32 v7, 16, v6
	v_add_u32_e32 v10, 64, v10
	v_cmp_lt_i32_e32 vcc, v7, v10
	v_and_b32_e32 v8, 0xffffffc0, v0
	v_lshlrev_b32_e32 v5, 2, v5
	v_cndmask_b32_e32 v7, v6, v7, vcc
	v_lshlrev_b32_e32 v82, 2, v7
	v_xor_b32_e32 v7, 32, v6
	v_lshlrev_b32_e32 v8, 2, v8
	v_cmp_lt_i32_e32 vcc, v7, v10
	v_add3_u32 v85, v9, v5, v8
	v_not_b32_e32 v5, 63
	v_cndmask_b32_e32 v6, v6, v7, vcc
	v_bitop3_b32 v5, v0, 15, v5 bitop3:0xe0
	v_readlane_b32 s53, v254, 22
	v_readlane_b32 s54, v254, 23
	v_readlane_b32 s55, v254, 24
	v_readlane_b32 s56, v254, 25
	v_readlane_b32 s57, v254, 26
	v_readlane_b32 s58, v254, 27
	v_readlane_b32 s59, v254, 28
	v_readlane_b32 s60, v254, 29
	v_readlane_b32 s61, v254, 30
	v_mov_b32_e32 v19, 0
	v_lshlrev_b32_e32 v83, 2, v6
	v_and_b32_e32 v6, 0xffffffcf, v0
	v_or_b32_e32 v8, 16, v5
	v_or_b32_e32 v10, 32, v5
	v_or_b32_e32 v12, 48, v5
	v_readlane_b32 s0, v254, 19
	v_readlane_b32 s8, v254, 7
	v_readlane_b32 s9, v254, 8
	v_ashrrev_i32_e32 v7, 31, v6
	v_ashrrev_i32_e32 v9, 31, v8
	v_ashrrev_i32_e32 v11, 31, v10
	v_ashrrev_i32_e32 v13, 31, v12
	v_readlane_b32 s52, v254, 39
	v_mov_b32_e32 v5, v19
	v_readlane_b32 s1, v254, 20
	v_readlane_b32 s6, v254, 5
	v_readlane_b32 s7, v254, 6
	v_add_u32_e32 v20, 0x700, v0
	v_add_u32_e32 v22, 0x840, v0
	v_add_u32_e32 v24, 0x940, v0
	v_lshlrev_b32_e32 v18, 2, v16
	v_lshlrev_b64 v[6:7], 8, v[6:7]
	v_lshlrev_b64 v[8:9], 8, v[8:9]
	v_lshlrev_b64 v[10:11], 8, v[10:11]
	v_lshlrev_b64 v[12:13], 8, v[12:13]
	v_readlane_b32 s62, v254, 49
	v_readlane_b32 s63, v254, 50
	v_lshl_add_u64 v[4:5], s[0:1], 0, v[4:5]
	v_lshlrev_b64 v[38:39], 1, v[0:1]
	s_mov_b32 s8, 0x358637bd
	v_and_b32_e32 v79, 7, v78
	s_mov_b32 s5, 0
	v_ashrrev_i32_e32 v21, 31, v20
	v_ashrrev_i32_e32 v23, 31, v22
	v_ashrrev_i32_e32 v25, 31, v24
	v_lshl_add_u32 v84, v0, 2, 0
	v_lshl_add_u64 v[26:27], s[80:81], 0, v[18:19]
	v_lshl_add_u64 v[28:29], s[62:63], 0, v[18:19]
	v_lshl_add_u64 v[30:31], v[4:5], 0, v[6:7]
	v_lshl_add_u64 v[32:33], v[4:5], 0, v[8:9]
	v_lshl_add_u64 v[34:35], v[4:5], 0, v[10:11]
	v_lshl_add_u64 v[36:37], v[4:5], 0, v[12:13]
	v_lshl_add_u64 v[40:41], s[40:41], 0, v[38:39]
	v_lshl_add_u64 v[42:43], s[44:45], 0, v[38:39]
	v_lshl_add_u64 v[44:45], s[62:63], 0, v[2:3]
	v_lshl_add_u64 v[46:47], s[42:43], 0, v[38:39]
	s_movk_i32 s3, 0x1e20
	s_movk_i32 s7, 0x1000
	s_mov_b32 s84, 0xbc800000
	s_mov_b32 s6, 0x3c800000
	s_mov_b32 s9, 0x3a27c5ac
	s_mov_b32 s85, 0x800000
	v_mov_b32_e32 v86, 0x1e20
	s_mov_b32 s86, s2
	v_readlane_b32 s10, v254, 9
	v_readlane_b32 s11, v254, 10
	v_readlane_b32 s12, v254, 11
	v_readlane_b32 s13, v254, 12
	v_readlane_b32 s14, v254, 13
	v_readlane_b32 s15, v254, 14
	v_readlane_b32 s16, v254, 15
	v_readlane_b32 s17, v254, 16
	v_readlane_b32 s18, v254, 17
	v_readlane_b32 s19, v254, 18
	v_readlane_b32 s53, v254, 40
	v_readlane_b32 s54, v254, 41
	v_readlane_b32 s55, v254, 42
	v_readlane_b32 s56, v254, 43
	v_readlane_b32 s57, v254, 44
	v_readlane_b32 s58, v254, 45
	v_readlane_b32 s59, v254, 46
	v_readlane_b32 s60, v254, 47
	v_readlane_b32 s61, v254, 48
	v_readlane_b32 s64, v254, 51
	v_readlane_b32 s65, v254, 52
	v_readlane_b32 s66, v254, 53
	v_readlane_b32 s67, v254, 54
	s_branch .LBB0_530

.LBB0_595:
	s_or_b64 exec, exec, s[0:1]
	s_setprio 0
	v_readlane_b32 s0, v254, 56
	v_readlane_b32 s1, v254, 57
	v_mov_b32_e32 v98, v174
	s_waitcnt lgkmcnt(0)
	v_mov_b32_e32 v0, v174
	v_cndmask_b32_e64 v1, 0, 1, s[0:1]
	s_barrier
	v_cmp_ne_u32_e64 s[96:97], 1, v1
	v_ashrrev_i32_e32 v99, 7, v0
	s_andn2_b64 vcc, exec, s[0:1]
	v_bfe_u32 v100, v0, 6, 1
	s_cbranch_vccnz .LBB0_604
	s_cmpk_gt_i32 s2, 0x10ff
	s_cbranch_scc1 .LBB0_603
	v_and_b32_e32 v0, 15, v98
	v_lshl_or_b32 v101, v99, 6, v0
	v_lshrrev_b32_e32 v0, 2, v98
	v_and_b32_e32 v0, 12, v0
	s_add_u32 s3, s36, 0x7c0000
	v_lshl_or_b32 v102, v100, 6, v0
	s_addc_u32 s88, s37, 0
	v_mov_b32_e32 v65, 0
	s_mov_b64 s[0:1], 0x80
	s_mov_b64 s[4:5], 0x7c0080
	s_mov_b64 s[6:7], 0x100
	s_mov_b64 s[8:9], 0x7c0100
	s_mov_b32 s89, s2
	s_waitcnt vmcnt(0)
	s_branch .LBB0_599

.LBB0_604:
.LBB0_605:
	s_ashr_i32 s3, s2, 3
	s_cmpk_gt_i32 s3, 0x21f
	s_cbranch_scc1 .LBB0_612
	s_and_b32 s88, s2, 7
	s_ashr_i32 s89, s28, 3
	v_and_b32_e32 v0, 15, v98
	v_lshl_or_b32 v99, v99, 6, v0
	v_lshrrev_b32_e32 v0, 2, v98
	s_add_u32 s90, s36, 0x7c0000
	v_and_b32_e32 v0, 12, v0
	s_addc_u32 s91, s37, 0
	s_lshl_b32 s0, s3, 3
	v_lshl_or_b32 v98, v100, 6, v0
	s_or_b32 s92, s0, s88
	v_mov_b32_e32 v65, 0
	s_mov_b64 s[0:1], 0x80
	s_mov_b64 s[4:5], 0x7c0080
	s_mov_b64 s[6:7], 0x100
	s_mov_b64 s[8:9], 0x7c0100
	s_waitcnt vmcnt(0)
	s_cmp_lt_u32 s2, 0x100
	s_cbranch_scc1 .Lgprio_1
	s_setprio 1
.Lgprio_1:
	s_branch .LBB0_608
.LBB0_607:
	v_mul_f32_e32 v60, 0xbfb8aa3b, v60
	v_exp_f32_e32 v60, v60
	v_mul_f32_e32 v56, 0xbfb8aa3b, v56
	v_mul_f32_e32 v57, 0xbfb8aa3b, v57
	v_mul_f32_e32 v58, 0xbfb8aa3b, v58
	v_add_f32_e32 v60, 1.0, v60
	v_rcp_f32_e32 v64, v60
	v_mul_f32_e32 v60, 0xbfb8aa3b, v61
	v_mul_f32_e32 v61, 0xbfb8aa3b, v62
	v_exp_f32_e32 v61, v61
	v_mul_f32_e32 v62, 0xbfb8aa3b, v63
	v_exp_f32_e32 v60, v60
	v_exp_f32_e32 v62, v62
	v_add_f32_e32 v61, 1.0, v61
	v_mul_f32_e32 v59, 0xbfb8aa3b, v59
	v_add_f32_e32 v60, 1.0, v60
	v_rcp_f32_e32 v63, v61
	v_add_f32_e32 v61, 1.0, v62
	v_exp_f32_e32 v56, v56
	v_exp_f32_e32 v57, v57
	v_exp_f32_e32 v58, v58
	v_exp_f32_e32 v59, v59
	v_rcp_f32_e32 v68, v61
	v_rcp_f32_e32 v70, v60
	v_add_f32_e32 v56, 1.0, v56
	v_add_f32_e32 v57, 1.0, v57
	v_add_f32_e32 v58, 1.0, v58
	v_add_f32_e32 v59, 1.0, v59
	v_mul_f32_e32 v52, 0xbfb8aa3b, v52
	v_mul_f32_e32 v53, 0xbfb8aa3b, v53
	v_mul_f32_e32 v54, 0xbfb8aa3b, v54
	v_mul_f32_e32 v55, 0xbfb8aa3b, v55
	v_lshl_add_u32 v66, s12, 7, v99
	v_cvt_pk_f16_f32 v69, v63, v68
	v_cvt_pk_f16_f32 v68, v64, v70
	v_rcp_f32_e32 v56, v56
	v_rcp_f32_e32 v58, v58
	v_rcp_f32_e32 v59, v59
	v_rcp_f32_e32 v64, v57
	v_exp_f32_e32 v52, v52
	v_exp_f32_e32 v53, v53
	v_exp_f32_e32 v54, v54
	v_exp_f32_e32 v55, v55
	v_ashrrev_i32_e32 v67, 31, v66
	v_lshl_or_b32 v62, s10, 7, v98
	v_mul_f32_e32 v50, 0xbfb8aa3b, v50
	v_mul_f32_e32 v51, 0xbfb8aa3b, v51
	v_lshlrev_b64 v[60:61], 13, v[66:67]
	v_ashrrev_i32_e32 v63, 31, v62
	v_exp_f32_e32 v50, v50
	v_exp_f32_e32 v51, v51
	v_lshl_add_u64 v[70:71], s[42:43], 0, v[60:61]
	v_lshlrev_b64 v[60:61], 1, v[62:63]
	v_lshl_add_u64 v[62:63], v[70:71], 0, v[60:61]
	v_cvt_pk_f16_f32 v57, v58, v59
	v_cvt_pk_f16_f32 v56, v56, v64
	v_add_f32_e32 v52, 1.0, v52
	v_add_f32_e32 v53, 1.0, v53
	v_add_f32_e32 v54, 1.0, v54
	v_add_f32_e32 v55, 1.0, v55
	v_mul_f32_e32 v48, 0xbfb8aa3b, v48
	v_mul_f32_e32 v49, 0xbfb8aa3b, v49
	s_waitcnt vmcnt(0)
	s_barrier
	global_store_dwordx2 v[62:63], v[56:57], off offset:32
	v_rcp_f32_e32 v52, v52
	v_rcp_f32_e32 v54, v54
	v_rcp_f32_e32 v55, v55
	v_rcp_f32_e32 v56, v53
	v_exp_f32_e32 v48, v48
	v_exp_f32_e32 v49, v49
	v_add_f32_e32 v50, 1.0, v50
	v_add_f32_e32 v51, 1.0, v51
	v_rcp_f32_e32 v50, v50
	v_rcp_f32_e32 v51, v51
	v_cvt_pk_f16_f32 v53, v54, v55
	v_cvt_pk_f16_f32 v52, v52, v56
	v_add_f32_e32 v48, 1.0, v48
	v_add_f32_e32 v49, 1.0, v49
	global_store_dwordx2 v[62:63], v[52:53], off offset:64
	v_rcp_f32_e32 v48, v48
	v_rcp_f32_e32 v52, v49
	v_mul_f32_e32 v44, 0xbfb8aa3b, v44
	v_mul_f32_e32 v45, 0xbfb8aa3b, v45
	v_mul_f32_e32 v46, 0xbfb8aa3b, v46
	v_mul_f32_e32 v47, 0xbfb8aa3b, v47
	v_cvt_pk_f16_f32 v49, v50, v51
	v_exp_f32_e32 v50, v44
	v_exp_f32_e32 v45, v45
	v_exp_f32_e32 v46, v46
	v_exp_f32_e32 v47, v47
	v_cvt_pk_f16_f32 v48, v48, v52
	global_store_dwordx2 v[62:63], v[48:49], off offset:96
	v_add_f32_e32 v48, 1.0, v50
	v_add_f32_e32 v45, 1.0, v45
	v_add_f32_e32 v46, 1.0, v46
	v_add_f32_e32 v47, 1.0, v47
	v_mul_f32_e32 v40, 0xbfb8aa3b, v40
	v_mul_f32_e32 v41, 0xbfb8aa3b, v41
	v_mul_f32_e32 v42, 0xbfb8aa3b, v42
	v_mul_f32_e32 v43, 0xbfb8aa3b, v43
	v_or_b32_e32 v44, 16, v66
	v_rcp_f32_e32 v48, v48
	v_rcp_f32_e32 v46, v46
	v_rcp_f32_e32 v47, v47
	v_rcp_f32_e32 v49, v45
	v_exp_f32_e32 v40, v40
	v_exp_f32_e32 v41, v41
	v_exp_f32_e32 v42, v42
	v_exp_f32_e32 v43, v43
	v_ashrrev_i32_e32 v45, 31, v44
	v_lshlrev_b64 v[44:45], 13, v[44:45]
	v_lshl_add_u64 v[44:45], s[42:43], 0, v[44:45]
	v_cvt_pk_f16_f32 v47, v46, v47
	v_cvt_pk_f16_f32 v46, v48, v49
	v_lshl_add_u64 v[44:45], v[44:45], 0, v[60:61]
	v_add_f32_e32 v40, 1.0, v40
	v_add_f32_e32 v41, 1.0, v41
	v_add_f32_e32 v42, 1.0, v42
	v_add_f32_e32 v43, 1.0, v43
	v_mul_f32_e32 v36, 0xbfb8aa3b, v36
	v_mul_f32_e32 v37, 0xbfb8aa3b, v37
	v_mul_f32_e32 v38, 0xbfb8aa3b, v38
	v_mul_f32_e32 v39, 0xbfb8aa3b, v39
	global_store_dwordx2 v[44:45], v[46:47], off
	v_rcp_f32_e32 v40, v40
	v_rcp_f32_e32 v42, v42
	v_rcp_f32_e32 v43, v43
	v_rcp_f32_e32 v46, v41
	v_exp_f32_e32 v36, v36
	v_exp_f32_e32 v37, v37
	v_exp_f32_e32 v38, v38
	v_exp_f32_e32 v39, v39
	v_mul_f32_e32 v34, 0xbfb8aa3b, v34
	v_mul_f32_e32 v35, 0xbfb8aa3b, v35
	v_exp_f32_e32 v34, v34
	v_exp_f32_e32 v35, v35
	v_cvt_pk_f16_f32 v41, v42, v43
	v_cvt_pk_f16_f32 v40, v40, v46
	v_add_f32_e32 v36, 1.0, v36
	v_add_f32_e32 v37, 1.0, v37
	v_add_f32_e32 v38, 1.0, v38
	v_add_f32_e32 v39, 1.0, v39
	v_mul_f32_e32 v32, 0xbfb8aa3b, v32
	v_mul_f32_e32 v33, 0xbfb8aa3b, v33
	global_store_dwordx2 v[44:45], v[40:41], off offset:32
	v_rcp_f32_e32 v36, v36
	v_rcp_f32_e32 v38, v38
	v_rcp_f32_e32 v39, v39
	v_rcp_f32_e32 v40, v37
	v_exp_f32_e32 v32, v32
	v_exp_f32_e32 v33, v33
	v_add_f32_e32 v34, 1.0, v34
	v_add_f32_e32 v35, 1.0, v35
	v_rcp_f32_e32 v34, v34
	v_rcp_f32_e32 v35, v35
	v_cvt_pk_f16_f32 v37, v38, v39
	v_cvt_pk_f16_f32 v36, v36, v40
	v_add_f32_e32 v32, 1.0, v32
	v_add_f32_e32 v33, 1.0, v33
	global_store_dwordx2 v[44:45], v[36:37], off offset:64
	v_rcp_f32_e32 v32, v32
	v_rcp_f32_e32 v36, v33
	v_mul_f32_e32 v28, 0xbfb8aa3b, v28
	v_mul_f32_e32 v29, 0xbfb8aa3b, v29
	v_mul_f32_e32 v30, 0xbfb8aa3b, v30
	v_mul_f32_e32 v31, 0xbfb8aa3b, v31
	v_cvt_pk_f16_f32 v33, v34, v35
	v_exp_f32_e32 v34, v28
	v_exp_f32_e32 v29, v29
	v_exp_f32_e32 v30, v30
	v_exp_f32_e32 v31, v31
	v_cvt_pk_f16_f32 v32, v32, v36
	global_store_dwordx2 v[44:45], v[32:33], off offset:96
	v_add_f32_e32 v32, 1.0, v34
	v_add_f32_e32 v29, 1.0, v29
	v_add_f32_e32 v30, 1.0, v30
	v_add_f32_e32 v31, 1.0, v31
	v_mul_f32_e32 v24, 0xbfb8aa3b, v24
	v_mul_f32_e32 v25, 0xbfb8aa3b, v25
	v_mul_f32_e32 v26, 0xbfb8aa3b, v26
	v_mul_f32_e32 v27, 0xbfb8aa3b, v27
	v_or_b32_e32 v28, 32, v66
	v_rcp_f32_e32 v32, v32
	v_rcp_f32_e32 v30, v30
	v_rcp_f32_e32 v31, v31
	v_rcp_f32_e32 v33, v29
	v_exp_f32_e32 v24, v24
	v_exp_f32_e32 v25, v25
	v_exp_f32_e32 v26, v26
	v_exp_f32_e32 v27, v27
	v_ashrrev_i32_e32 v29, 31, v28
	v_lshlrev_b64 v[28:29], 13, v[28:29]
	v_lshl_add_u64 v[28:29], s[42:43], 0, v[28:29]
	v_cvt_pk_f16_f32 v31, v30, v31
	v_cvt_pk_f16_f32 v30, v32, v33
	v_lshl_add_u64 v[28:29], v[28:29], 0, v[60:61]
	v_add_f32_e32 v24, 1.0, v24
	v_add_f32_e32 v25, 1.0, v25
	v_add_f32_e32 v26, 1.0, v26
	v_add_f32_e32 v27, 1.0, v27
	v_mul_f32_e32 v20, 0xbfb8aa3b, v20
	v_mul_f32_e32 v21, 0xbfb8aa3b, v21
	v_mul_f32_e32 v22, 0xbfb8aa3b, v22
	v_mul_f32_e32 v23, 0xbfb8aa3b, v23
	global_store_dwordx2 v[28:29], v[30:31], off
	v_rcp_f32_e32 v24, v24
	v_rcp_f32_e32 v26, v26
	v_rcp_f32_e32 v27, v27
	v_rcp_f32_e32 v30, v25
	v_exp_f32_e32 v20, v20
	v_exp_f32_e32 v21, v21
	v_exp_f32_e32 v22, v22
	v_exp_f32_e32 v23, v23
	v_mul_f32_e32 v18, 0xbfb8aa3b, v18
	v_mul_f32_e32 v19, 0xbfb8aa3b, v19
	v_exp_f32_e32 v18, v18
	v_exp_f32_e32 v19, v19
	v_cvt_pk_f16_f32 v25, v26, v27
	v_cvt_pk_f16_f32 v24, v24, v30
	v_add_f32_e32 v20, 1.0, v20
	v_add_f32_e32 v21, 1.0, v21
	v_add_f32_e32 v22, 1.0, v22
	v_add_f32_e32 v23, 1.0, v23
	v_mul_f32_e32 v16, 0xbfb8aa3b, v16
	v_mul_f32_e32 v17, 0xbfb8aa3b, v17
	global_store_dwordx2 v[28:29], v[24:25], off offset:32
	v_rcp_f32_e32 v20, v20
	v_rcp_f32_e32 v22, v22
	v_rcp_f32_e32 v23, v23
	v_rcp_f32_e32 v24, v21
	v_exp_f32_e32 v16, v16
	v_exp_f32_e32 v17, v17
	v_add_f32_e32 v18, 1.0, v18
	v_add_f32_e32 v19, 1.0, v19
	v_rcp_f32_e32 v18, v18
	v_rcp_f32_e32 v19, v19
	v_cvt_pk_f16_f32 v21, v22, v23
	v_cvt_pk_f16_f32 v20, v20, v24
	v_add_f32_e32 v16, 1.0, v16
	v_add_f32_e32 v17, 1.0, v17
	global_store_dwordx2 v[28:29], v[20:21], off offset:64
	v_rcp_f32_e32 v16, v16
	v_rcp_f32_e32 v20, v17
	v_mul_f32_e32 v12, 0xbfb8aa3b, v12
	v_mul_f32_e32 v13, 0xbfb8aa3b, v13
	v_mul_f32_e32 v14, 0xbfb8aa3b, v14
	v_mul_f32_e32 v15, 0xbfb8aa3b, v15
	v_cvt_pk_f16_f32 v17, v18, v19
	v_exp_f32_e32 v18, v12
	v_exp_f32_e32 v13, v13
	v_exp_f32_e32 v14, v14
	v_exp_f32_e32 v15, v15
	v_cvt_pk_f16_f32 v16, v16, v20
	global_store_dwordx2 v[28:29], v[16:17], off offset:96
	v_add_f32_e32 v16, 1.0, v18
	v_add_f32_e32 v13, 1.0, v13
	v_add_f32_e32 v14, 1.0, v14
	v_add_f32_e32 v15, 1.0, v15
	v_mul_f32_e32 v8, 0xbfb8aa3b, v8
	v_mul_f32_e32 v9, 0xbfb8aa3b, v9
	v_mul_f32_e32 v10, 0xbfb8aa3b, v10
	v_mul_f32_e32 v11, 0xbfb8aa3b, v11
	v_or_b32_e32 v12, 48, v66
	v_rcp_f32_e32 v16, v16
	v_rcp_f32_e32 v14, v14
	v_rcp_f32_e32 v15, v15
	v_rcp_f32_e32 v17, v13
	v_exp_f32_e32 v8, v8
	v_exp_f32_e32 v9, v9
	v_exp_f32_e32 v10, v10
	v_exp_f32_e32 v11, v11
	v_mul_f32_e32 v6, 0xbfb8aa3b, v6
	v_mul_f32_e32 v7, 0xbfb8aa3b, v7
	v_ashrrev_i32_e32 v13, 31, v12
	v_exp_f32_e32 v6, v6
	v_exp_f32_e32 v7, v7
	v_lshlrev_b64 v[12:13], 13, v[12:13]
	v_lshl_add_u64 v[12:13], s[42:43], 0, v[12:13]
	v_cvt_pk_f16_f32 v15, v14, v15
	v_cvt_pk_f16_f32 v14, v16, v17
	v_lshl_add_u64 v[12:13], v[12:13], 0, v[60:61]
	v_add_f32_e32 v8, 1.0, v8
	v_add_f32_e32 v9, 1.0, v9
	v_add_f32_e32 v10, 1.0, v10
	v_add_f32_e32 v11, 1.0, v11
	v_mul_f32_e32 v4, 0xbfb8aa3b, v4
	v_mul_f32_e32 v5, 0xbfb8aa3b, v5
	v_mul_f32_e32 v0, 0xbfb8aa3b, v0
	v_mul_f32_e32 v1, 0xbfb8aa3b, v1
	v_mul_f32_e32 v2, 0xbfb8aa3b, v2
	v_mul_f32_e32 v3, 0xbfb8aa3b, v3
	global_store_dwordx2 v[12:13], v[14:15], off
	v_rcp_f32_e32 v8, v8
	v_rcp_f32_e32 v10, v10
	v_rcp_f32_e32 v11, v11
	v_rcp_f32_e32 v14, v9
	v_exp_f32_e32 v4, v4
	v_exp_f32_e32 v5, v5
	v_add_f32_e32 v6, 1.0, v6
	v_add_f32_e32 v7, 1.0, v7
	v_exp_f32_e32 v0, v0
	v_exp_f32_e32 v1, v1
	v_exp_f32_e32 v2, v2
	v_exp_f32_e32 v3, v3
	v_rcp_f32_e32 v6, v6
	v_rcp_f32_e32 v7, v7
	v_cvt_pk_f16_f32 v9, v10, v11
	v_cvt_pk_f16_f32 v8, v8, v14
	v_add_f32_e32 v4, 1.0, v4
	v_add_f32_e32 v5, 1.0, v5
	v_add_f32_e32 v0, 1.0, v0
	v_add_f32_e32 v1, 1.0, v1
	v_add_f32_e32 v2, 1.0, v2
	v_add_f32_e32 v3, 1.0, v3
	global_store_dwordx2 v[12:13], v[8:9], off offset:32
	v_rcp_f32_e32 v4, v4
	v_rcp_f32_e32 v8, v5
	v_cvt_pk_f16_f32 v5, v6, v7
	v_rcp_f32_e32 v0, v0
	v_rcp_f32_e32 v2, v2
	v_rcp_f32_e32 v3, v3
	v_rcp_f32_e32 v6, v1
	s_add_i32 s3, s3, s89
	s_add_i32 s92, s92, s28
	v_cvt_pk_f16_f32 v4, v4, v8
	v_cvt_pk_f16_f32 v1, v2, v3
	v_cvt_pk_f16_f32 v0, v0, v6
	s_cmpk_gt_i32 s3, 0x21f
	global_store_dwordx2 v[62:63], v[68:69], off
	global_store_dwordx2 v[12:13], v[4:5], off offset:64
	global_store_dwordx2 v[12:13], v[0:1], off offset:96
	s_cbranch_scc1 .LBB0_612

.LBB0_664:
	s_or_b64 exec, exec, s[0:1]
	s_setprio 0
	v_mov_b32_e32 v176, v174
	s_waitcnt lgkmcnt(0)
	v_mov_b32_e32 v0, v174
	s_barrier
	s_and_b64 vcc, exec, s[96:97]
	v_ashrrev_i32_e32 v177, 7, v0
	v_bfe_u32 v178, v0, 6, 1
	s_cbranch_vccnz .LBB0_675
	s_and_b64 vcc, exec, s[30:31]
	s_cbranch_vccnz .LBB0_674
	v_and_b32_e32 v0, 15, v176
	v_lshl_or_b32 v179, v177, 6, v0
	v_lshrrev_b32_e32 v0, 2, v176
	v_and_b32_e32 v0, 12, v0
	s_add_u32 s3, s36, 0xfc0000
	v_lshl_or_b32 v180, v178, 6, v0
	s_addc_u32 s86, s37, 0
	s_mov_b32 s1, 0
	v_mov_b32_e32 v1, 0
	s_mov_b64 s[4:5], 0x80
	s_mov_b64 s[6:7], 0xfc0080
	s_mov_b64 s[8:9], 0x100
	s_mov_b64 s[10:11], 0xfc0100
	s_mov_b32 s87, s2
	s_branch .LBB0_668

.LBB0_675:
.LBB0_676:
	s_ashr_i32 s3, s2, 3
	s_cmpk_gt_i32 s3, 0x87
	s_cbranch_scc1 .LBB0_685
	s_and_b32 s86, s2, 7
	s_ashr_i32 s87, s28, 3
	v_and_b32_e32 v0, 15, v176
	v_lshl_or_b32 v177, v177, 6, v0
	v_lshrrev_b32_e32 v0, 2, v176
	s_add_u32 s88, s36, 0xfc0000
	v_and_b32_e32 v0, 12, v0
	s_addc_u32 s89, s37, 0
	s_lshl_b32 s0, s3, 3
	v_lshl_or_b32 v176, v178, 6, v0
	s_or_b32 s90, s0, s86
	s_mov_b32 s1, 0
	v_mov_b32_e32 v1, 0
	s_mov_b64 s[4:5], 0x80
	s_mov_b64 s[6:7], 0xfc0080
	s_mov_b64 s[8:9], 0x100
	s_mov_b64 s[10:11], 0xfc0100
	s_cmp_lt_u32 s2, 0x100
	s_cbranch_scc1 .Lgprio_2
	s_setprio 1
.Lgprio_2:
	s_branch .LBB0_679
.LBB0_678:
	v_lshlrev_b64 v[2:3], 11, v[132:133]
	v_cvt_pk_f16_f32 v67, v66, v67
	v_cvt_pk_f16_f32 v66, v64, v65
	v_lshl_add_u64 v[2:3], s[38:39], 0, v[2:3]
	v_lshlrev_b64 v[64:65], 1, v[134:135]
	v_lshl_add_u64 v[2:3], v[2:3], 0, v[64:65]
	v_cvt_pk_f16_f32 v63, v62, v63
	v_cvt_pk_f16_f32 v62, v60, v61
	v_cvt_pk_f16_f32 v59, v58, v59
	v_cvt_pk_f16_f32 v58, v56, v57
	v_cvt_pk_f16_f32 v55, v54, v55
	v_cvt_pk_f16_f32 v54, v52, v53
	s_waitcnt vmcnt(0)
	s_barrier
	global_store_dwordx2 v[2:3], v[66:67], off
	global_store_dwordx2 v[2:3], v[62:63], off offset:32
	global_store_dwordx2 v[2:3], v[58:59], off offset:64
	global_store_dwordx2 v[2:3], v[54:55], off offset:96
	v_or_b32_e32 v2, 16, v132
	v_ashrrev_i32_e32 v3, 31, v2
	v_lshlrev_b64 v[2:3], 11, v[2:3]
	v_lshl_add_u64 v[2:3], s[38:39], 0, v[2:3]
	v_cvt_pk_f16_f32 v51, v50, v51
	v_cvt_pk_f16_f32 v50, v48, v49
	v_lshl_add_u64 v[2:3], v[2:3], 0, v[64:65]
	v_cvt_pk_f16_f32 v47, v46, v47
	v_cvt_pk_f16_f32 v46, v44, v45
	v_cvt_pk_f16_f32 v43, v42, v43
	v_cvt_pk_f16_f32 v42, v40, v41
	v_cvt_pk_f16_f32 v39, v38, v39
	v_cvt_pk_f16_f32 v38, v36, v37
	global_store_dwordx2 v[2:3], v[50:51], off
	global_store_dwordx2 v[2:3], v[46:47], off offset:32
	global_store_dwordx2 v[2:3], v[42:43], off offset:64
	global_store_dwordx2 v[2:3], v[38:39], off offset:96
	v_or_b32_e32 v2, 32, v132
	v_ashrrev_i32_e32 v3, 31, v2
	v_lshlrev_b64 v[2:3], 11, v[2:3]
	v_lshl_add_u64 v[2:3], s[38:39], 0, v[2:3]
	v_cvt_pk_f16_f32 v35, v34, v35
	v_cvt_pk_f16_f32 v34, v32, v33
	v_lshl_add_u64 v[2:3], v[2:3], 0, v[64:65]
	v_cvt_pk_f16_f32 v31, v30, v31
	v_cvt_pk_f16_f32 v30, v28, v29
	v_cvt_pk_f16_f32 v27, v26, v27
	v_cvt_pk_f16_f32 v26, v24, v25
	v_cvt_pk_f16_f32 v23, v22, v23
	v_cvt_pk_f16_f32 v22, v20, v21
	global_store_dwordx2 v[2:3], v[34:35], off
	global_store_dwordx2 v[2:3], v[30:31], off offset:32
	global_store_dwordx2 v[2:3], v[26:27], off offset:64
	global_store_dwordx2 v[2:3], v[22:23], off offset:96
	v_or_b32_e32 v2, 48, v132
	v_ashrrev_i32_e32 v3, 31, v2
	v_lshlrev_b64 v[2:3], 11, v[2:3]
	v_lshl_add_u64 v[2:3], s[38:39], 0, v[2:3]
	s_add_i32 s3, s3, s87
	s_add_i32 s90, s90, s28
	v_cvt_pk_f16_f32 v19, v18, v19
	v_cvt_pk_f16_f32 v18, v16, v17
	v_lshl_add_u64 v[2:3], v[2:3], 0, v[64:65]
	v_cvt_pk_f16_f32 v15, v14, v15
	v_cvt_pk_f16_f32 v14, v12, v13
	v_cvt_pk_f16_f32 v11, v10, v11
	v_cvt_pk_f16_f32 v10, v8, v9
	v_cvt_pk_f16_f32 v7, v6, v7
	v_cvt_pk_f16_f32 v6, v4, v5
	s_cmpk_gt_i32 s3, 0x87
	global_store_dwordx2 v[2:3], v[18:19], off
	global_store_dwordx2 v[2:3], v[14:15], off offset:32
	global_store_dwordx2 v[2:3], v[10:11], off offset:64
	global_store_dwordx2 v[2:3], v[6:7], off offset:96
	s_cbranch_scc1 .LBB0_685

.LBB0_737:
	v_writelane_b32 v255, s68, 26
	s_nop 1
	v_writelane_b32 v255, s69, 27
	v_writelane_b32 v255, s70, 28
	v_writelane_b32 v255, s71, 29
	v_writelane_b32 v255, s72, 30
	v_writelane_b32 v255, s73, 31
	v_writelane_b32 v255, s74, 32
	v_writelane_b32 v255, s75, 33
	v_writelane_b32 v255, s76, 34
	v_writelane_b32 v255, s77, 35
	v_writelane_b32 v255, s78, 36
	v_writelane_b32 v255, s79, 37
	v_writelane_b32 v255, s80, 38
	v_writelane_b32 v255, s81, 39
	v_writelane_b32 v255, s82, 40
	v_writelane_b32 v255, s83, 41
	s_or_b64 exec, exec, s[0:1]
	s_setprio 0
	s_add_u32 s70, s36, 0x11c0000
	v_mov_b32_e32 v98, v174
	s_waitcnt lgkmcnt(0)
	v_mov_b32_e32 v0, v174
	s_barrier
	s_addc_u32 s71, s37, 0
	s_and_b64 vcc, exec, s[96:97]
	v_ashrrev_i32_e32 v99, 7, v0
	v_bfe_u32 v100, v0, 6, 1
	s_cbranch_vccnz .LBB0_746
	s_and_b64 vcc, exec, s[30:31]
	s_cbranch_vccnz .LBB0_745
	v_and_b32_e32 v0, 15, v98
	v_lshl_or_b32 v101, v99, 6, v0
	v_lshrrev_b32_e32 v0, 2, v98
	v_and_b32_e32 v0, 12, v0
	v_lshl_or_b32 v102, v100, 6, v0
	v_mov_b32_e32 v65, 0
	s_movk_i32 s3, 0x4000
	s_mov_b64 s[0:1], 0x80
	s_mov_b64 s[4:5], 0x11c0080
	s_mov_b64 s[6:7], 0x100
	s_mov_b64 s[8:9], 0x11c0100
	s_mov_b32 s90, s2
	s_branch .LBB0_741

.LBB0_746:
.LBB0_747:
	s_ashr_i32 s3, s2, 3
	s_cmpk_gt_i32 s3, 0x87
	s_cbranch_scc1 .LBB0_754
	v_and_b32_e32 v0, 15, v98
	v_lshl_or_b32 v99, v99, 6, v0
	v_lshrrev_b32_e32 v0, 2, v98
	s_and_b32 s90, s2, 7
	v_and_b32_e32 v0, 12, v0
	s_lshl_b32 s0, s3, 3
	s_ashr_i32 s91, s28, 3
	v_lshl_or_b32 v98, v100, 6, v0
	s_or_b32 s92, s0, s90
	v_mov_b32_e32 v65, 0
	s_movk_i32 s93, 0x4000
	s_mov_b64 s[0:1], 0x80
	s_mov_b64 s[4:5], 0x11c0080
	s_mov_b64 s[6:7], 0x100
	s_mov_b64 s[8:9], 0x11c0100
	s_cmp_lt_u32 s2, 0x100
	s_cbranch_scc1 .Lgprio_3
	s_setprio 1
.Lgprio_3:
	s_branch .LBB0_750
.LBB0_749:
	v_lshl_add_u32 v66, s12, 7, v99
	v_ashrrev_i32_e32 v64, 31, v66
	v_cmp_gt_i32_e32 vcc, s93, v66
	v_readlane_b32 s52, v254, 39
	v_add_u32_e32 v68, 0xffffc000, v66
	v_cndmask_b32_e32 v67, 0, v64, vcc
	v_readlane_b32 s53, v254, 40
	v_readlane_b32 s54, v254, 41
	v_readlane_b32 s55, v254, 42
	v_cndmask_b32_e32 v68, v68, v66, vcc
	v_mov_b32_e32 v69, v67
	v_mov_b32_e32 v64, s55
	v_mov_b32_e32 v78, s53
	v_mov_b32_e32 v79, s54
	v_mov_b32_e32 v80, s52
	v_cndmask_b32_e32 v71, v64, v78, vcc
	v_cndmask_b32_e32 v70, v79, v80, vcc
	v_lshlrev_b64 v[68:69], 12, v[68:69]
	v_lshl_add_u64 v[68:69], v[70:71], 0, v[68:69]
	v_lshl_or_b32 v70, s10, 7, v98
	v_ashrrev_i32_e32 v71, 31, v70
	v_lshlrev_b64 v[72:73], 2, v[70:71]
	v_lshl_add_u64 v[74:75], v[68:69], 0, v[72:73]
	s_waitcnt vmcnt(0)
	s_barrier
	global_load_dwordx4 v[68:71], v[74:75], off nt
	v_readlane_b32 s12, v254, 3
	v_lshlrev_b64 v[76:77], 12, v[66:67]
	v_readlane_b32 s26, v254, 17
	v_readlane_b32 s27, v254, 18
	s_add_i32 s3, s3, s91
	s_add_i32 s92, s92, s28
	v_lshl_add_u64 v[76:77], s[26:27], 0, v[76:77]
	v_lshl_add_u64 v[76:77], v[76:77], 0, v[72:73]
	s_cmpk_gt_i32 s3, 0x87
	v_readlane_b32 s56, v254, 43
	v_readlane_b32 s57, v254, 44
	v_readlane_b32 s58, v254, 45
	v_readlane_b32 s59, v254, 46
	v_readlane_b32 s60, v254, 47
	v_readlane_b32 s61, v254, 48
	v_readlane_b32 s62, v254, 49
	v_readlane_b32 s63, v254, 50
	v_readlane_b32 s64, v254, 51
	v_readlane_b32 s65, v254, 52
	v_readlane_b32 s66, v254, 53
	v_readlane_b32 s67, v254, 54
	v_readlane_b32 s13, v254, 4
	v_readlane_b32 s14, v254, 5
	v_readlane_b32 s15, v254, 6
	v_readlane_b32 s16, v254, 7
	v_readlane_b32 s17, v254, 8
	v_readlane_b32 s18, v254, 9
	v_readlane_b32 s19, v254, 10
	v_readlane_b32 s20, v254, 11
	v_readlane_b32 s21, v254, 12
	v_readlane_b32 s22, v254, 13
	v_readlane_b32 s23, v254, 14
	v_readlane_b32 s24, v254, 15
	v_readlane_b32 s25, v254, 16
	s_waitcnt vmcnt(0)
	v_pk_add_f32 v[62:63], v[62:63], v[70:71]
	v_pk_add_f32 v[60:61], v[60:61], v[68:69]
	global_store_dwordx4 v[76:77], v[60:63], off
	global_load_dwordx4 v[60:63], v[74:75], off offset:64 nt
	s_waitcnt vmcnt(0)
	v_pk_add_f32 v[58:59], v[58:59], v[62:63]
	v_pk_add_f32 v[56:57], v[56:57], v[60:61]
	global_store_dwordx4 v[76:77], v[56:59], off offset:64
	global_load_dwordx4 v[56:59], v[74:75], off offset:128 nt
	s_waitcnt vmcnt(0)
	v_pk_add_f32 v[54:55], v[54:55], v[58:59]
	v_pk_add_f32 v[52:53], v[52:53], v[56:57]
	global_store_dwordx4 v[76:77], v[52:55], off offset:128
	global_load_dwordx4 v[52:55], v[74:75], off offset:192 nt
	v_or_b32_e32 v56, 16, v66
	v_ashrrev_i32_e32 v57, 31, v56
	v_cmp_gt_i32_e32 vcc, s93, v56
	v_add_u32_e32 v58, 0xffffc010, v66
	s_waitcnt vmcnt(0)
	v_pk_add_f32 v[50:51], v[50:51], v[54:55]
	v_cndmask_b32_e32 v57, 0, v57, vcc
	v_cndmask_b32_e32 v58, v58, v56, vcc
	v_mov_b32_e32 v59, v57
	v_cndmask_b32_e32 v61, v64, v78, vcc
	v_cndmask_b32_e32 v60, v79, v80, vcc
	v_lshlrev_b64 v[58:59], 12, v[58:59]
	v_lshl_add_u64 v[58:59], v[60:61], 0, v[58:59]
	v_pk_add_f32 v[48:49], v[48:49], v[52:53]
	v_lshl_add_u64 v[58:59], v[58:59], 0, v[72:73]
	global_store_dwordx4 v[76:77], v[48:51], off offset:192
	global_load_dwordx4 v[48:51], v[58:59], off nt
	v_lshlrev_b64 v[52:53], 12, v[56:57]
	v_lshl_add_u64 v[52:53], s[26:27], 0, v[52:53]
	v_lshl_add_u64 v[52:53], v[52:53], 0, v[72:73]
	s_waitcnt vmcnt(0)
	v_pk_add_f32 v[46:47], v[46:47], v[50:51]
	v_pk_add_f32 v[44:45], v[44:45], v[48:49]
	global_store_dwordx4 v[52:53], v[44:47], off
	global_load_dwordx4 v[44:47], v[58:59], off offset:64 nt
	s_waitcnt vmcnt(0)
	v_pk_add_f32 v[42:43], v[42:43], v[46:47]
	v_pk_add_f32 v[40:41], v[40:41], v[44:45]
	global_store_dwordx4 v[52:53], v[40:43], off offset:64
	global_load_dwordx4 v[40:43], v[58:59], off offset:128 nt
	s_waitcnt vmcnt(0)
	v_pk_add_f32 v[38:39], v[38:39], v[42:43]
	v_pk_add_f32 v[36:37], v[36:37], v[40:41]
	global_store_dwordx4 v[52:53], v[36:39], off offset:128
	global_load_dwordx4 v[36:39], v[58:59], off offset:192 nt
	v_or_b32_e32 v40, 32, v66
	v_ashrrev_i32_e32 v41, 31, v40
	v_cmp_gt_i32_e32 vcc, s93, v40
	v_add_u32_e32 v42, 0xffffc020, v66
	s_waitcnt vmcnt(0)
	v_pk_add_f32 v[34:35], v[34:35], v[38:39]
	v_cndmask_b32_e32 v41, 0, v41, vcc
	v_cndmask_b32_e32 v42, v42, v40, vcc
	v_mov_b32_e32 v43, v41
	v_cndmask_b32_e32 v45, v64, v78, vcc
	v_cndmask_b32_e32 v44, v79, v80, vcc
	v_lshlrev_b64 v[42:43], 12, v[42:43]
	v_lshl_add_u64 v[42:43], v[44:45], 0, v[42:43]
	v_pk_add_f32 v[32:33], v[32:33], v[36:37]
	v_lshl_add_u64 v[42:43], v[42:43], 0, v[72:73]
	global_store_dwordx4 v[52:53], v[32:35], off offset:192
	global_load_dwordx4 v[32:35], v[42:43], off nt
	v_lshlrev_b64 v[36:37], 12, v[40:41]
	v_lshl_add_u64 v[36:37], s[26:27], 0, v[36:37]
	v_lshl_add_u64 v[36:37], v[36:37], 0, v[72:73]
	s_waitcnt vmcnt(0)
	v_pk_add_f32 v[30:31], v[30:31], v[34:35]
	v_pk_add_f32 v[28:29], v[28:29], v[32:33]
	global_store_dwordx4 v[36:37], v[28:31], off
	global_load_dwordx4 v[28:31], v[42:43], off offset:64 nt
	s_waitcnt vmcnt(0)
	v_pk_add_f32 v[26:27], v[26:27], v[30:31]
	v_pk_add_f32 v[24:25], v[24:25], v[28:29]
	global_store_dwordx4 v[36:37], v[24:27], off offset:64
	global_load_dwordx4 v[24:27], v[42:43], off offset:128 nt
	s_waitcnt vmcnt(0)
	v_pk_add_f32 v[22:23], v[22:23], v[26:27]
	v_pk_add_f32 v[20:21], v[20:21], v[24:25]
	global_store_dwordx4 v[36:37], v[20:23], off offset:128
	global_load_dwordx4 v[20:23], v[42:43], off offset:192 nt
	v_or_b32_e32 v24, 48, v66
	v_ashrrev_i32_e32 v25, 31, v24
	v_cmp_gt_i32_e32 vcc, s93, v24
	v_add_u32_e32 v26, 0xffffc030, v66
	s_waitcnt vmcnt(0)
	v_pk_add_f32 v[18:19], v[18:19], v[22:23]
	v_cndmask_b32_e32 v25, 0, v25, vcc
	v_cndmask_b32_e32 v26, v26, v24, vcc
	v_mov_b32_e32 v27, v25
	v_cndmask_b32_e32 v29, v64, v78, vcc
	v_cndmask_b32_e32 v28, v79, v80, vcc
	v_lshlrev_b64 v[26:27], 12, v[26:27]
	v_lshl_add_u64 v[26:27], v[28:29], 0, v[26:27]
	v_pk_add_f32 v[16:17], v[16:17], v[20:21]
	v_lshl_add_u64 v[26:27], v[26:27], 0, v[72:73]
	global_store_dwordx4 v[36:37], v[16:19], off offset:192
	global_load_dwordx4 v[16:19], v[26:27], off nt
	v_lshlrev_b64 v[20:21], 12, v[24:25]
	v_lshl_add_u64 v[20:21], s[26:27], 0, v[20:21]
	v_lshl_add_u64 v[20:21], v[20:21], 0, v[72:73]
	s_waitcnt vmcnt(0)
	v_pk_add_f32 v[14:15], v[14:15], v[18:19]
	v_pk_add_f32 v[12:13], v[12:13], v[16:17]
	global_store_dwordx4 v[20:21], v[12:15], off
	global_load_dwordx4 v[12:15], v[26:27], off offset:64 nt
	s_waitcnt vmcnt(0)
	v_pk_add_f32 v[10:11], v[10:11], v[14:15]
	v_pk_add_f32 v[8:9], v[8:9], v[12:13]
	global_store_dwordx4 v[20:21], v[8:11], off offset:64
	global_load_dwordx4 v[8:11], v[26:27], off offset:128 nt
	s_waitcnt vmcnt(0)
	v_pk_add_f32 v[6:7], v[6:7], v[10:11]
	v_pk_add_f32 v[4:5], v[4:5], v[8:9]
	global_store_dwordx4 v[20:21], v[4:7], off offset:128
	global_load_dwordx4 v[4:7], v[26:27], off offset:192 nt
	s_waitcnt vmcnt(0)
	v_pk_add_f32 v[2:3], v[2:3], v[6:7]
	v_pk_add_f32 v[0:1], v[0:1], v[4:5]
	global_store_dwordx4 v[20:21], v[0:3], off offset:192
	s_cbranch_scc1 .LBB0_754

.LBB0_806:
	s_or_b64 exec, exec, s[0:1]
	s_setprio 0
	s_waitcnt lgkmcnt(0)
	v_mov_b32_e32 v0, v174
	v_mov_b32_e32 v1, v174
	s_barrier
	v_readlane_b32 s0, v254, 55
	v_ashrrev_i32_e32 v1, 6, v1
	s_movk_i32 s3, 0x4400
	v_add_u32_e32 v46, s0, v1
	v_cmp_gt_i32_e32 vcc, s3, v46
	s_and_saveexec_b64 s[4:5], vcc
	s_cbranch_execz .LBB0_817
	v_mbcnt_hi_u32_b32 v1, -1, v175
	v_and_b32_e32 v3, 64, v1
	v_xor_b32_e32 v2, 16, v1
	v_add_u32_e32 v3, 64, v3
	v_cmp_lt_i32_e32 vcc, v2, v3
	v_lshlrev_b32_e32 v0, 2, v0
	v_and_b32_e32 v0, 0xfc, v0
	v_cndmask_b32_e32 v2, v1, v2, vcc
	v_readlane_b32 s12, v254, 3
	s_waitcnt vmcnt(4)
	v_lshlrev_b32_e32 v55, 2, v2
	v_xor_b32_e32 v2, 32, v1
	v_mov_b32_e32 v49, 0
	v_lshlrev_b32_e32 v48, 2, v0
	v_readlane_b32 s18, v254, 9
	v_readlane_b32 s19, v254, 10
	v_cmp_lt_i32_e32 vcc, v2, v3
	s_lshl_b32 s10, s28, 2
	v_lshl_add_u64 v[50:51], s[18:19], 0, v[48:49]
	v_cndmask_b32_e32 v1, v1, v2, vcc
	v_lshlrev_b32_e32 v48, 1, v0
	v_lshlrev_b32_e32 v64, 2, v1
	v_lshl_add_u64 v[52:53], s[38:39], 0, v[48:49]
	s_mov_b64 s[8:9], 0
	s_movk_i32 s11, 0x43ff
	v_lshlrev_b32_e32 v48, 2, v0
	v_mov_b32_e32 v54, 0x358637bd
	s_mov_b32 s12, 0x800000
	v_readlane_b32 s13, v254, 4
	v_readlane_b32 s14, v254, 5
	v_readlane_b32 s15, v254, 6
	v_readlane_b32 s16, v254, 7
	v_readlane_b32 s17, v254, 8
	v_readlane_b32 s20, v254, 11
	v_readlane_b32 s21, v254, 12
	v_readlane_b32 s22, v254, 13
	v_readlane_b32 s23, v254, 14
	v_readlane_b32 s24, v254, 15
	v_readlane_b32 s25, v254, 16
	v_readlane_b32 s26, v254, 17
	v_readlane_b32 s27, v254, 18
	s_branch .LBB0_809

.LBB0_869:
	s_or_b64 exec, exec, s[0:1]
	s_setprio 0
	v_mov_b32_e32 v98, v174
	s_waitcnt lgkmcnt(0)
	v_mov_b32_e32 v0, v174
	s_barrier
	s_and_b64 vcc, exec, s[96:97]
	v_ashrrev_i32_e32 v99, 7, v0
	v_bfe_u32 v100, v0, 6, 1
	s_cbranch_vccnz .LBB0_878
	s_cmpk_gt_i32 s2, 0x175f
	s_cbranch_scc1 .LBB0_877
	v_and_b32_e32 v0, 15, v98
	v_lshl_or_b32 v101, v99, 6, v0
	v_lshrrev_b32_e32 v0, 2, v98
	v_and_b32_e32 v0, 12, v0
	s_add_u32 s3, s36, 0x13c0000
	v_lshl_or_b32 v102, v100, 5, v0
	s_addc_u32 s90, s37, 0
	v_mov_b32_e32 v65, 0
	s_mov_b64 s[0:1], 0x80
	s_mov_b64 s[4:5], 0x13c0080
	s_mov_b64 s[6:7], 0x100
	s_mov_b64 s[8:9], 0x13c0100
	s_movk_i32 s91, 0x1600
	s_mov_b32 s92, s2
	s_waitcnt vmcnt(0)
	s_branch .LBB0_873

.LBB0_878:
.LBB0_879:
	s_ashr_i32 s3, s2, 3
	s_cmpk_gt_i32 s3, 0x2eb
	s_cbranch_scc1 .LBB0_886
	s_and_b32 s90, s2, 7
	s_ashr_i32 s91, s28, 3
	v_and_b32_e32 v0, 15, v98
	v_lshl_or_b32 v99, v99, 6, v0
	v_lshrrev_b32_e32 v0, 2, v98
	s_add_u32 s92, s36, 0x13c0000
	v_and_b32_e32 v0, 12, v0
	s_addc_u32 s93, s37, 0
	s_lshl_b32 s0, s3, 3
	v_lshl_or_b32 v98, v100, 5, v0
	s_or_b32 s94, s0, s90
	v_mov_b32_e32 v65, 0
	s_mov_b64 s[0:1], 0x80
	s_mov_b64 s[4:5], 0x13c0080
	s_mov_b64 s[6:7], 0x100
	s_mov_b64 s[8:9], 0x13c0100
	s_movk_i32 s95, 0x1600
	s_waitcnt vmcnt(0)
	s_cmp_lt_u32 s2, 0x100
	s_cbranch_scc1 .Lgprio_4
	s_setprio 1
.Lgprio_4:
	s_branch .LBB0_882
.LBB0_881:
	v_mul_f32_e32 v66, 0xbfb8aa3b, v60
	v_mul_f32_e32 v67, 0xbfb8aa3b, v61
	v_exp_f32_e32 v66, v66
	v_exp_f32_e32 v67, v67
	v_lshl_add_u32 v64, s12, 7, v99
	s_waitcnt vmcnt(0)
	v_add_f32_e32 v66, 1.0, v66
	v_add_f32_e32 v67, 1.0, v67
	v_rcp_f32_e32 v66, v66
	v_rcp_f32_e32 v67, v67
	s_barrier
	s_add_i32 s3, s3, s91
	v_pk_mul_f32 v[60:61], v[60:61], v[66:67]
	s_add_i32 s94, s94, s28
	v_pk_mul_f32 v[56:57], v[56:57], v[60:61]
	s_cmpk_gt_i32 s3, 0x2eb
	v_cvt_pk_f16_f32 v60, v56, v57
	v_mul_f32_e32 v56, 0xbfb8aa3b, v62
	v_mul_f32_e32 v57, 0xbfb8aa3b, v63
	v_exp_f32_e32 v56, v56
	v_exp_f32_e32 v57, v57
	v_add_f32_e32 v56, 1.0, v56
	v_add_f32_e32 v57, 1.0, v57
	v_rcp_f32_e32 v56, v56
	v_rcp_f32_e32 v57, v57
	s_nop 0
	v_pk_mul_f32 v[56:57], v[62:63], v[56:57]
	s_nop 0
	v_pk_mul_f32 v[56:57], v[58:59], v[56:57]
	v_lshl_or_b32 v58, s10, 6, v98
	v_cvt_pk_f16_f32 v61, v56, v57
	v_mov_b64_e32 v[56:57], s[42:43]
	v_ashrrev_i32_e32 v59, 31, v58
	v_mad_i64_i32 v[62:63], s[10:11], v64, s95, v[56:57]
	v_lshlrev_b64 v[58:59], 1, v[58:59]
	v_lshl_add_u64 v[62:63], v[62:63], 0, v[58:59]
	global_store_dwordx2 v[62:63], v[60:61], off
	v_mul_f32_e32 v60, 0xbfb8aa3b, v52
	v_mul_f32_e32 v61, 0xbfb8aa3b, v53
	v_exp_f32_e32 v60, v60
	v_exp_f32_e32 v61, v61
	v_add_f32_e32 v60, 1.0, v60
	v_add_f32_e32 v61, 1.0, v61
	v_rcp_f32_e32 v60, v60
	v_rcp_f32_e32 v61, v61
	s_nop 0
	v_pk_mul_f32 v[52:53], v[52:53], v[60:61]
	s_nop 0
	v_pk_mul_f32 v[48:49], v[48:49], v[52:53]
	s_nop 0
	v_cvt_pk_f16_f32 v48, v48, v49
	v_mul_f32_e32 v49, 0xbfb8aa3b, v54
	v_exp_f32_e32 v49, v49
	s_nop 0
	v_add_f32_e32 v49, 1.0, v49
	v_rcp_f32_e32 v52, v49
	v_mul_f32_e32 v49, 0xbfb8aa3b, v55
	v_exp_f32_e32 v49, v49
	s_nop 0
	v_add_f32_e32 v49, 1.0, v49
	v_rcp_f32_e32 v53, v49
	s_nop 0
	v_pk_mul_f32 v[52:53], v[54:55], v[52:53]
	s_nop 0
	v_pk_mul_f32 v[50:51], v[50:51], v[52:53]
	s_nop 0
	v_cvt_pk_f16_f32 v49, v50, v51
	global_store_dwordx2 v[62:63], v[48:49], off offset:32
	v_mul_f32_e32 v48, 0xbfb8aa3b, v44
	v_mul_f32_e32 v49, 0xbfb8aa3b, v45
	v_exp_f32_e32 v48, v48
	v_exp_f32_e32 v49, v49
	v_or_b32_e32 v50, 16, v64
	v_add_f32_e32 v48, 1.0, v48
	v_add_f32_e32 v49, 1.0, v49
	v_rcp_f32_e32 v48, v48
	v_rcp_f32_e32 v49, v49
	s_nop 0
	v_pk_mul_f32 v[44:45], v[44:45], v[48:49]
	s_nop 0
	v_pk_mul_f32 v[40:41], v[40:41], v[44:45]
	s_nop 0
	v_cvt_pk_f16_f32 v40, v40, v41
	v_mul_f32_e32 v41, 0xbfb8aa3b, v46
	v_exp_f32_e32 v41, v41
	s_nop 0
	v_add_f32_e32 v41, 1.0, v41
	v_rcp_f32_e32 v44, v41
	v_mul_f32_e32 v41, 0xbfb8aa3b, v47
	v_exp_f32_e32 v41, v41
	s_nop 0
	v_add_f32_e32 v41, 1.0, v41
	v_rcp_f32_e32 v45, v41
	s_nop 0
	v_pk_mul_f32 v[44:45], v[46:47], v[44:45]
	s_nop 0
	v_pk_mul_f32 v[42:43], v[42:43], v[44:45]
	s_nop 0
	v_cvt_pk_f16_f32 v41, v42, v43
	v_mad_i64_i32 v[42:43], s[10:11], v50, s95, v[56:57]
	v_lshl_add_u64 v[42:43], v[42:43], 0, v[58:59]
	global_store_dwordx2 v[42:43], v[40:41], off
	v_mul_f32_e32 v40, 0xbfb8aa3b, v36
	v_mul_f32_e32 v41, 0xbfb8aa3b, v37
	v_exp_f32_e32 v40, v40
	v_exp_f32_e32 v41, v41
	v_add_f32_e32 v40, 1.0, v40
	v_add_f32_e32 v41, 1.0, v41
	v_rcp_f32_e32 v40, v40
	v_rcp_f32_e32 v41, v41
	s_nop 0
	v_pk_mul_f32 v[36:37], v[36:37], v[40:41]
	s_nop 0
	v_pk_mul_f32 v[32:33], v[32:33], v[36:37]
	s_nop 0
	v_cvt_pk_f16_f32 v32, v32, v33
	v_mul_f32_e32 v33, 0xbfb8aa3b, v38
	v_exp_f32_e32 v33, v33
	s_nop 0
	v_add_f32_e32 v33, 1.0, v33
	v_rcp_f32_e32 v36, v33
	v_mul_f32_e32 v33, 0xbfb8aa3b, v39
	v_exp_f32_e32 v33, v33
	s_nop 0
	v_add_f32_e32 v33, 1.0, v33
	v_rcp_f32_e32 v37, v33
	s_nop 0
	v_pk_mul_f32 v[36:37], v[38:39], v[36:37]
	s_nop 0
	v_pk_mul_f32 v[34:35], v[34:35], v[36:37]
	s_nop 0
	v_cvt_pk_f16_f32 v33, v34, v35
	global_store_dwordx2 v[42:43], v[32:33], off offset:32
	v_mul_f32_e32 v32, 0xbfb8aa3b, v28
	v_mul_f32_e32 v33, 0xbfb8aa3b, v29
	v_exp_f32_e32 v32, v32
	v_exp_f32_e32 v33, v33
	v_or_b32_e32 v34, 32, v64
	v_add_f32_e32 v32, 1.0, v32
	v_add_f32_e32 v33, 1.0, v33
	v_rcp_f32_e32 v32, v32
	v_rcp_f32_e32 v33, v33
	s_nop 0
	v_pk_mul_f32 v[28:29], v[28:29], v[32:33]
	s_nop 0
	v_pk_mul_f32 v[24:25], v[24:25], v[28:29]
	s_nop 0
	v_cvt_pk_f16_f32 v24, v24, v25
	v_mul_f32_e32 v25, 0xbfb8aa3b, v30
	v_exp_f32_e32 v25, v25
	s_nop 0
	v_add_f32_e32 v25, 1.0, v25
	v_rcp_f32_e32 v28, v25
	v_mul_f32_e32 v25, 0xbfb8aa3b, v31
	v_exp_f32_e32 v25, v25
	s_nop 0
	v_add_f32_e32 v25, 1.0, v25
	v_rcp_f32_e32 v29, v25
	s_nop 0
	v_pk_mul_f32 v[28:29], v[30:31], v[28:29]
	s_nop 0
	v_pk_mul_f32 v[26:27], v[26:27], v[28:29]
	s_nop 0
	v_cvt_pk_f16_f32 v25, v26, v27
	v_mad_i64_i32 v[26:27], s[10:11], v34, s95, v[56:57]
	v_lshl_add_u64 v[26:27], v[26:27], 0, v[58:59]
	global_store_dwordx2 v[26:27], v[24:25], off
	v_mul_f32_e32 v24, 0xbfb8aa3b, v20
	v_mul_f32_e32 v25, 0xbfb8aa3b, v21
	v_exp_f32_e32 v24, v24
	v_exp_f32_e32 v25, v25
	v_add_f32_e32 v24, 1.0, v24
	v_add_f32_e32 v25, 1.0, v25
	v_rcp_f32_e32 v24, v24
	v_rcp_f32_e32 v25, v25
	s_nop 0
	v_pk_mul_f32 v[20:21], v[20:21], v[24:25]
	s_nop 0
	v_pk_mul_f32 v[16:17], v[16:17], v[20:21]
	s_nop 0
	v_cvt_pk_f16_f32 v16, v16, v17
	v_mul_f32_e32 v17, 0xbfb8aa3b, v22
	v_exp_f32_e32 v17, v17
	s_nop 0
	v_add_f32_e32 v17, 1.0, v17
	v_rcp_f32_e32 v20, v17
	v_mul_f32_e32 v17, 0xbfb8aa3b, v23
	v_exp_f32_e32 v17, v17
	s_nop 0
	v_add_f32_e32 v17, 1.0, v17
	v_rcp_f32_e32 v21, v17
	s_nop 0
	v_pk_mul_f32 v[20:21], v[22:23], v[20:21]
	s_nop 0
	v_pk_mul_f32 v[18:19], v[18:19], v[20:21]
	s_nop 0
	v_cvt_pk_f16_f32 v17, v18, v19
	global_store_dwordx2 v[26:27], v[16:17], off offset:32
	v_mul_f32_e32 v16, 0xbfb8aa3b, v12
	v_mul_f32_e32 v17, 0xbfb8aa3b, v13
	v_exp_f32_e32 v16, v16
	v_exp_f32_e32 v17, v17
	v_or_b32_e32 v18, 48, v64
	v_add_f32_e32 v16, 1.0, v16
	v_add_f32_e32 v17, 1.0, v17
	v_rcp_f32_e32 v16, v16
	v_rcp_f32_e32 v17, v17
	s_nop 0
	v_pk_mul_f32 v[12:13], v[12:13], v[16:17]
	s_nop 0
	v_pk_mul_f32 v[8:9], v[8:9], v[12:13]
	s_nop 0
	v_cvt_pk_f16_f32 v8, v8, v9
	v_mul_f32_e32 v9, 0xbfb8aa3b, v14
	v_exp_f32_e32 v9, v9
	s_nop 0
	v_add_f32_e32 v9, 1.0, v9
	v_rcp_f32_e32 v12, v9
	v_mul_f32_e32 v9, 0xbfb8aa3b, v15
	v_exp_f32_e32 v9, v9
	s_nop 0
	v_add_f32_e32 v9, 1.0, v9
	v_rcp_f32_e32 v13, v9
	s_nop 0
	v_pk_mul_f32 v[12:13], v[14:15], v[12:13]
	s_nop 0
	v_pk_mul_f32 v[10:11], v[10:11], v[12:13]
	s_nop 0
	v_cvt_pk_f16_f32 v9, v10, v11
	v_mad_i64_i32 v[10:11], s[10:11], v18, s95, v[56:57]
	v_lshl_add_u64 v[10:11], v[10:11], 0, v[58:59]
	global_store_dwordx2 v[10:11], v[8:9], off
	v_mul_f32_e32 v8, 0xbfb8aa3b, v4
	v_mul_f32_e32 v9, 0xbfb8aa3b, v5
	v_exp_f32_e32 v8, v8
	v_exp_f32_e32 v9, v9
	v_add_f32_e32 v8, 1.0, v8
	v_add_f32_e32 v9, 1.0, v9
	v_rcp_f32_e32 v8, v8
	v_rcp_f32_e32 v9, v9
	s_nop 0
	v_pk_mul_f32 v[4:5], v[4:5], v[8:9]
	s_nop 0
	v_pk_mul_f32 v[0:1], v[0:1], v[4:5]
	s_nop 0
	v_cvt_pk_f16_f32 v0, v0, v1
	v_mul_f32_e32 v1, 0xbfb8aa3b, v6
	v_exp_f32_e32 v1, v1
	s_nop 0
	v_add_f32_e32 v1, 1.0, v1
	v_rcp_f32_e32 v4, v1
	v_mul_f32_e32 v1, 0xbfb8aa3b, v7
	v_exp_f32_e32 v1, v1
	s_nop 0
	v_add_f32_e32 v1, 1.0, v1
	v_rcp_f32_e32 v5, v1
	s_nop 0
	v_pk_mul_f32 v[4:5], v[6:7], v[4:5]
	s_nop 0
	v_pk_mul_f32 v[2:3], v[2:3], v[4:5]
	s_nop 0
	v_cvt_pk_f16_f32 v1, v2, v3
	global_store_dwordx2 v[10:11], v[0:1], off offset:32
	s_cbranch_scc1 .LBB0_886

.LBB0_938:
	s_or_b64 exec, exec, s[0:1]
	s_setprio 0
	s_add_u32 s88, s36, 0x1ec0000
	v_mov_b32_e32 v98, v174
	s_waitcnt lgkmcnt(0)
	v_mov_b32_e32 v0, v174
	s_barrier
	s_addc_u32 s89, s37, 0
	s_and_b64 vcc, exec, s[96:97]
	v_ashrrev_i32_e32 v99, 7, v0
	v_bfe_u32 v100, v0, 6, 1
	s_cbranch_vccnz .LBB0_947
	s_and_b64 vcc, exec, s[30:31]
	s_cbranch_vccnz .LBB0_946
	v_and_b32_e32 v0, 15, v98
	v_lshl_or_b32 v101, v99, 6, v0
	v_lshrrev_b32_e32 v0, 2, v98
	v_and_b32_e32 v0, 12, v0
	v_lshl_or_b32 v102, v100, 6, v0
	v_mov_b32_e32 v65, 0
	s_mov_b64 s[0:1], 0x80
	s_mov_b64 s[4:5], 0x1ec0080
	s_mov_b64 s[6:7], 0x100
	s_mov_b64 s[8:9], 0x1ec0100
	s_mov_b32 s3, s2
	s_branch .LBB0_942

.LBB0_947:
.LBB0_948:
	s_ashr_i32 s3, s2, 3
	s_cmpk_gt_i32 s3, 0x87
	s_cbranch_scc1 .LBB0_955
	v_and_b32_e32 v0, 15, v98
	v_lshl_or_b32 v99, v99, 6, v0
	v_lshrrev_b32_e32 v0, 2, v98
	s_and_b32 s84, s2, 7
	v_and_b32_e32 v0, 12, v0
	s_lshl_b32 s0, s3, 3
	s_ashr_i32 s85, s28, 3
	v_lshl_or_b32 v98, v100, 6, v0
	s_or_b32 s90, s0, s84
	v_mov_b32_e32 v65, 0
	s_mov_b64 s[0:1], 0x80
	s_mov_b64 s[4:5], 0x1ec0080
	s_mov_b64 s[6:7], 0x100
	s_mov_b64 s[8:9], 0x1ec0100
	s_cmp_lt_u32 s2, 0x100
	s_cbranch_scc1 .Lgprio_5
	s_setprio 1
.Lgprio_5:
	s_branch .LBB0_951
.LBB0_950:
	v_lshl_add_u32 v66, s92, 7, v99
	v_ashrrev_i32_e32 v67, 31, v66
	v_readlane_b32 s12, v254, 3
	v_lshlrev_b64 v[68:69], 12, v[66:67]
	v_readlane_b32 s26, v254, 17
	v_readlane_b32 s27, v254, 18
	s_waitcnt vmcnt(0)
	s_barrier
	v_lshl_add_u64 v[70:71], s[26:27], 0, v[68:69]
	v_lshl_or_b32 v68, s91, 7, v98
	v_ashrrev_i32_e32 v69, 31, v68
	v_lshlrev_b64 v[68:69], 2, v[68:69]
	v_lshl_add_u64 v[74:75], v[70:71], 0, v[68:69]
	global_load_dwordx4 v[70:73], v[74:75], off
	s_add_i32 s3, s3, s85
	s_add_i32 s90, s90, s28
	s_cmpk_gt_i32 s3, 0x87
	v_readlane_b32 s13, v254, 4
	v_readlane_b32 s14, v254, 5
	v_readlane_b32 s15, v254, 6
	v_readlane_b32 s16, v254, 7
	v_readlane_b32 s17, v254, 8
	v_readlane_b32 s18, v254, 9
	v_readlane_b32 s19, v254, 10
	v_readlane_b32 s20, v254, 11
	v_readlane_b32 s21, v254, 12
	v_readlane_b32 s22, v254, 13
	v_readlane_b32 s23, v254, 14
	v_readlane_b32 s24, v254, 15
	v_readlane_b32 s25, v254, 16
	s_waitcnt vmcnt(0)
	v_pk_add_f32 v[60:61], v[60:61], v[70:71]
	v_pk_add_f32 v[62:63], v[62:63], v[72:73]
	global_store_dwordx4 v[74:75], v[60:63], off
	global_load_dwordx4 v[60:63], v[74:75], off offset:64
	s_waitcnt vmcnt(0)
	v_pk_add_f32 v[56:57], v[56:57], v[60:61]
	v_pk_add_f32 v[58:59], v[58:59], v[62:63]
	global_store_dwordx4 v[74:75], v[56:59], off offset:64
	global_load_dwordx4 v[56:59], v[74:75], off offset:128
	s_waitcnt vmcnt(0)
	v_pk_add_f32 v[52:53], v[52:53], v[56:57]
	v_pk_add_f32 v[54:55], v[54:55], v[58:59]
	global_store_dwordx4 v[74:75], v[52:55], off offset:128
	global_load_dwordx4 v[52:55], v[74:75], off offset:192
	s_waitcnt vmcnt(0)
	v_pk_add_f32 v[48:49], v[48:49], v[52:53]
	v_pk_add_f32 v[50:51], v[50:51], v[54:55]
	global_store_dwordx4 v[74:75], v[48:51], off offset:192
	s_nop 1
	v_or_b32_e32 v48, 16, v66
	v_ashrrev_i32_e32 v49, 31, v48
	v_lshlrev_b64 v[48:49], 12, v[48:49]
	v_lshl_add_u64 v[48:49], s[26:27], 0, v[48:49]
	v_lshl_add_u64 v[52:53], v[48:49], 0, v[68:69]
	global_load_dwordx4 v[48:51], v[52:53], off
	s_waitcnt vmcnt(0)
	v_pk_add_f32 v[44:45], v[44:45], v[48:49]
	v_pk_add_f32 v[46:47], v[46:47], v[50:51]
	global_store_dwordx4 v[52:53], v[44:47], off
	global_load_dwordx4 v[44:47], v[52:53], off offset:64
	s_waitcnt vmcnt(0)
	v_pk_add_f32 v[40:41], v[40:41], v[44:45]
	v_pk_add_f32 v[42:43], v[42:43], v[46:47]
	global_store_dwordx4 v[52:53], v[40:43], off offset:64
	global_load_dwordx4 v[40:43], v[52:53], off offset:128
	s_waitcnt vmcnt(0)
	v_pk_add_f32 v[36:37], v[36:37], v[40:41]
	v_pk_add_f32 v[38:39], v[38:39], v[42:43]
	global_store_dwordx4 v[52:53], v[36:39], off offset:128
	global_load_dwordx4 v[36:39], v[52:53], off offset:192
	s_waitcnt vmcnt(0)
	v_pk_add_f32 v[32:33], v[32:33], v[36:37]
	v_pk_add_f32 v[34:35], v[34:35], v[38:39]
	global_store_dwordx4 v[52:53], v[32:35], off offset:192
	s_nop 1
	v_or_b32_e32 v32, 32, v66
	v_ashrrev_i32_e32 v33, 31, v32
	v_lshlrev_b64 v[32:33], 12, v[32:33]
	v_lshl_add_u64 v[32:33], s[26:27], 0, v[32:33]
	v_lshl_add_u64 v[36:37], v[32:33], 0, v[68:69]
	global_load_dwordx4 v[32:35], v[36:37], off
	s_waitcnt vmcnt(0)
	v_pk_add_f32 v[28:29], v[28:29], v[32:33]
	v_pk_add_f32 v[30:31], v[30:31], v[34:35]
	global_store_dwordx4 v[36:37], v[28:31], off
	global_load_dwordx4 v[28:31], v[36:37], off offset:64
	s_waitcnt vmcnt(0)
	v_pk_add_f32 v[24:25], v[24:25], v[28:29]
	v_pk_add_f32 v[26:27], v[26:27], v[30:31]
	global_store_dwordx4 v[36:37], v[24:27], off offset:64
	global_load_dwordx4 v[24:27], v[36:37], off offset:128
	s_waitcnt vmcnt(0)
	v_pk_add_f32 v[20:21], v[20:21], v[24:25]
	v_pk_add_f32 v[22:23], v[22:23], v[26:27]
	global_store_dwordx4 v[36:37], v[20:23], off offset:128
	global_load_dwordx4 v[20:23], v[36:37], off offset:192
	s_waitcnt vmcnt(0)
	v_pk_add_f32 v[16:17], v[16:17], v[20:21]
	v_pk_add_f32 v[18:19], v[18:19], v[22:23]
	global_store_dwordx4 v[36:37], v[16:19], off offset:192
	s_nop 1
	v_or_b32_e32 v16, 48, v66
	v_ashrrev_i32_e32 v17, 31, v16
	v_lshlrev_b64 v[16:17], 12, v[16:17]
	v_lshl_add_u64 v[16:17], s[26:27], 0, v[16:17]
	v_lshl_add_u64 v[16:17], v[16:17], 0, v[68:69]
	global_load_dwordx4 v[18:21], v[16:17], off
	s_waitcnt vmcnt(0)
	v_pk_add_f32 v[12:13], v[12:13], v[18:19]
	v_pk_add_f32 v[14:15], v[14:15], v[20:21]
	global_store_dwordx4 v[16:17], v[12:15], off
	global_load_dwordx4 v[12:15], v[16:17], off offset:64
	s_waitcnt vmcnt(0)
	v_pk_add_f32 v[8:9], v[8:9], v[12:13]
	v_pk_add_f32 v[10:11], v[10:11], v[14:15]
	global_store_dwordx4 v[16:17], v[8:11], off offset:64
	global_load_dwordx4 v[8:11], v[16:17], off offset:128
	s_waitcnt vmcnt(0)
	v_pk_add_f32 v[4:5], v[4:5], v[8:9]
	v_pk_add_f32 v[6:7], v[6:7], v[10:11]
	global_store_dwordx4 v[16:17], v[4:7], off offset:128
	global_load_dwordx4 v[4:7], v[16:17], off offset:192
	s_waitcnt vmcnt(0)
	v_pk_add_f32 v[0:1], v[0:1], v[4:5]
	v_pk_add_f32 v[2:3], v[2:3], v[6:7]
	global_store_dwordx4 v[16:17], v[0:3], off offset:192
	s_cbranch_scc1 .LBB0_955

.LBB0_1007:
	s_or_b64 exec, exec, s[0:1]
	s_setprio 0
	v_mov_b32_e32 v10, v174
	v_readlane_b32 s0, v255, 42
	s_waitcnt lgkmcnt(0)
	s_barrier
	s_nop 0
	v_add_u32_e32 v11, s0, v10
	s_movk_i32 s0, 0x2000
	v_cmp_gt_i32_e32 vcc, s0, v11
	s_and_saveexec_b64 s[0:1], vcc
	s_cbranch_execz .LBB0_1014
	s_lshl_b32 s3, s28, 8
	v_readlane_b32 s4, v254, 19
	v_readlane_b32 s5, v254, 20
	s_add_u32 s4, s4, 0x10000
	v_readlane_b32 s52, v254, 21
	s_addc_u32 s5, s5, 0
	v_readlane_b32 s58, v254, 27
	v_readlane_b32 s59, v254, 28
	s_add_u32 s6, s58, 0x20000
	v_lshlrev_b32_e32 v0, 3, v10
	s_addc_u32 s7, s59, 0
	s_waitcnt vmcnt(10)
	v_lshl_add_u32 v12, s2, 11, v0
	s_lshl_b32 s12, s28, 11
	s_mov_b64 s[8:9], 0
	v_mov_b32_e32 v1, 0
	s_movk_i32 s13, 0x800
	v_readlane_b32 s53, v254, 22
	v_readlane_b32 s54, v254, 23
	v_readlane_b32 s55, v254, 24
	v_readlane_b32 s56, v254, 25
	v_readlane_b32 s57, v254, 26
	v_readlane_b32 s60, v254, 29
	v_readlane_b32 s61, v254, 30
	v_readlane_b32 s62, v254, 31
	v_readlane_b32 s63, v254, 32
	v_readlane_b32 s64, v254, 33
	v_readlane_b32 s65, v254, 34
	v_readlane_b32 s66, v254, 35
	v_readlane_b32 s67, v254, 36
	s_branch .LBB0_1010

.LBB0_1127:
	s_or_b64 exec, exec, s[0:1]
	s_setprio 0
	v_mov_b32_e32 v98, v174
	s_waitcnt lgkmcnt(0)
	v_mov_b32_e32 v0, v174
	s_barrier
	s_and_b64 vcc, exec, s[96:97]
	v_ashrrev_i32_e32 v99, 7, v0
	v_bfe_u32 v100, v0, 6, 1
	s_cbranch_vccnz .LBB0_1136
	s_cmpk_gt_i32 s2, 0xfef
	s_cbranch_scc1 .LBB0_1135
	v_and_b32_e32 v0, 15, v98
	v_lshl_or_b32 v101, v99, 6, v0
	v_lshrrev_b32_e32 v0, 2, v98
	v_and_b32_e32 v0, 12, v0
	v_lshl_or_b32 v102, v100, 6, v0
	v_mov_b32_e32 v65, 0
	s_mov_b64 s[0:1], 0x80
	s_mov_b64 s[4:5], 0x100
	s_movk_i32 s3, 0x1e20
	s_mov_b32 s18, s2
	s_waitcnt vmcnt(0)
	s_branch .LBB0_1131

.LBB0_1136:
.LBB0_1137:
	s_ashr_i32 s3, s2, 3
	s_cmpk_gt_i32 s3, 0x1fd
	s_cbranch_scc1 .LBB0_1144
	v_and_b32_e32 v0, 15, v98
	v_lshl_or_b32 v99, v99, 6, v0
	v_lshrrev_b32_e32 v0, 2, v98
	s_and_b32 s18, s2, 7
	v_and_b32_e32 v0, 12, v0
	s_lshl_b32 s0, s3, 3
	s_ashr_i32 s19, s28, 3
	v_lshl_or_b32 v98, v100, 6, v0
	s_or_b32 s20, s0, s18
	v_mov_b32_e32 v65, 0
	s_mov_b64 s[0:1], 0x80
	s_mov_b64 s[4:5], 0x100
	s_movk_i32 s21, 0x1e20
	s_waitcnt vmcnt(0)
	s_cmp_lt_u32 s2, 0x100
	s_cbranch_scc1 .Lgprio_6
	s_setprio 1
.Lgprio_6:
	s_branch .LBB0_1140
.LBB0_1139:
	v_lshl_add_u32 v64, s8, 7, v99
	v_lshl_or_b32 v66, s6, 7, v98
	v_cvt_pk_f16_f32 v63, v62, v63
	v_cvt_pk_f16_f32 v62, v60, v61
	v_mov_b64_e32 v[60:61], s[42:43]
	v_ashrrev_i32_e32 v67, 31, v66
	v_cvt_pk_f16_f32 v51, v50, v51
	v_cvt_pk_f16_f32 v50, v48, v49
	v_or_b32_e32 v48, 16, v64
	v_cvt_pk_f16_f32 v35, v34, v35
	v_cvt_pk_f16_f32 v34, v32, v33
	v_or_b32_e32 v32, 32, v64
	v_cvt_pk_f16_f32 v19, v18, v19
	v_cvt_pk_f16_f32 v18, v16, v17
	v_or_b32_e32 v16, 48, v64
	v_mad_i64_i32 v[68:69], s[6:7], v64, s21, v[60:61]
	v_lshlrev_b64 v[66:67], 1, v[66:67]
	v_cvt_pk_f16_f32 v47, v46, v47
	v_cvt_pk_f16_f32 v46, v44, v45
	v_mad_i64_i32 v[44:45], s[6:7], v48, s21, v[60:61]
	v_cvt_pk_f16_f32 v31, v30, v31
	v_cvt_pk_f16_f32 v30, v28, v29
	v_mad_i64_i32 v[28:29], s[6:7], v32, s21, v[60:61]
	v_cvt_pk_f16_f32 v15, v14, v15
	v_cvt_pk_f16_f32 v14, v12, v13
	v_mad_i64_i32 v[12:13], s[6:7], v16, s21, v[60:61]
	s_add_i32 s3, s3, s19
	s_add_i32 s20, s20, s28
	v_lshl_add_u64 v[68:69], v[68:69], 0, v[66:67]
	v_cvt_pk_f16_f32 v59, v58, v59
	v_cvt_pk_f16_f32 v58, v56, v57
	v_cvt_pk_f16_f32 v55, v54, v55
	v_cvt_pk_f16_f32 v54, v52, v53
	v_lshl_add_u64 v[44:45], v[44:45], 0, v[66:67]
	v_cvt_pk_f16_f32 v43, v42, v43
	v_cvt_pk_f16_f32 v42, v40, v41
	v_cvt_pk_f16_f32 v39, v38, v39
	v_cvt_pk_f16_f32 v38, v36, v37
	v_lshl_add_u64 v[28:29], v[28:29], 0, v[66:67]
	v_cvt_pk_f16_f32 v27, v26, v27
	v_cvt_pk_f16_f32 v26, v24, v25
	v_cvt_pk_f16_f32 v23, v22, v23
	v_cvt_pk_f16_f32 v22, v20, v21
	v_lshl_add_u64 v[12:13], v[12:13], 0, v[66:67]
	v_cvt_pk_f16_f32 v11, v10, v11
	v_cvt_pk_f16_f32 v10, v8, v9
	v_cvt_pk_f16_f32 v7, v6, v7
	v_cvt_pk_f16_f32 v6, v4, v5
	v_cvt_pk_f16_f32 v3, v2, v3
	v_cvt_pk_f16_f32 v2, v0, v1
	s_cmpk_gt_i32 s3, 0x1fd
	s_waitcnt vmcnt(0)
	s_barrier
	global_store_dwordx2 v[68:69], v[62:63], off
	global_store_dwordx2 v[68:69], v[58:59], off offset:32
	global_store_dwordx2 v[68:69], v[54:55], off offset:64
	global_store_dwordx2 v[68:69], v[50:51], off offset:96
	global_store_dwordx2 v[44:45], v[46:47], off
	global_store_dwordx2 v[44:45], v[42:43], off offset:32
	global_store_dwordx2 v[44:45], v[38:39], off offset:64
	global_store_dwordx2 v[44:45], v[34:35], off offset:96
	global_store_dwordx2 v[28:29], v[30:31], off
	global_store_dwordx2 v[28:29], v[26:27], off offset:32
	global_store_dwordx2 v[28:29], v[22:23], off offset:64
	global_store_dwordx2 v[28:29], v[18:19], off offset:96
	global_store_dwordx2 v[12:13], v[14:15], off
	global_store_dwordx2 v[12:13], v[10:11], off offset:32
	global_store_dwordx2 v[12:13], v[6:7], off offset:64
	global_store_dwordx2 v[12:13], v[2:3], off offset:96
	s_cbranch_scc1 .LBB0_1144

.LBB0_1196:
	s_or_b64 exec, exec, s[0:1]
	s_setprio 0
	v_readlane_b32 s0, v254, 58
	v_writelane_b32 v255, s30, 42
	v_readlane_b32 s1, v254, 59
	s_waitcnt lgkmcnt(0)
	v_mov_b32_e32 v0, v174
	v_writelane_b32 v255, s31, 43
	s_andn2_b64 vcc, exec, s[0:1]
	s_barrier
	s_cbranch_vccnz .LBB0_1207
	v_max_i32_e32 v1, 0x300, v0
	v_sub_u32_e32 v1, v1, v0
	v_add_u32_e32 v1, 0xff, v1
	v_lshrrev_b32_e32 v2, 8, v1
	s_movk_i32 s0, 0x400
	v_add_u32_e32 v2, 1, v2
	v_cmp_gt_i32_e32 vcc, s0, v0
	s_movk_i32 s0, 0xff
	s_waitcnt vmcnt(5)
	v_and_b32_e32 v6, 0x1fffffe, v2
	s_add_u32 s3, s42, 0xe00
	v_cmp_lt_u32_e64 s[0:1], s0, v1
	v_lshl_add_u32 v7, v6, 8, v0
	v_add_u32_e32 v1, 0x100, v0
	v_cmp_ne_u32_e64 s[6:7], v2, v6
	s_addc_u32 s26, s43, 0
	s_mov_b32 s27, s2
	s_branch .LBB0_1199

.LBB0_1268:
	s_or_b64 exec, exec, s[0:1]
	s_setprio 0
	v_readlane_b32 s52, v255, 26
	v_readlane_b32 s58, v255, 32
	v_readlane_b32 s59, v255, 33
	s_add_u32 s92, s58, 0x2000
	s_addc_u32 s93, s59, 0
	s_add_u32 s0, s58, 0x3000
	s_addc_u32 s1, s59, 0
	v_writelane_b32 v254, s0, 37
	v_readlane_b32 s53, v255, 27
	v_readlane_b32 s54, v255, 28
	v_writelane_b32 v254, s1, 38
	s_add_u32 s0, s58, 0x2200
	s_addc_u32 s1, s59, 0
	v_writelane_b32 v254, s0, 58
	v_readlane_b32 s55, v255, 29
	v_readlane_b32 s56, v255, 30
	v_writelane_b32 v254, s1, 59
	s_add_u32 s0, s58, 0x3200
	s_addc_u32 s1, s59, 0
	v_readlane_b32 s57, v255, 31
	v_readlane_b32 s60, v255, 34
	v_readlane_b32 s61, v255, 35
	v_readlane_b32 s62, v255, 36
	v_readlane_b32 s63, v255, 37
	v_readlane_b32 s64, v255, 38
	v_readlane_b32 s65, v255, 39
	v_readlane_b32 s66, v255, 40
	v_readlane_b32 s67, v255, 41
	v_writelane_b32 v255, s0, 20
	s_mov_b32 s11, 0
	v_mov_b32_e32 v28, 0
	v_writelane_b32 v255, s1, 21
	s_add_u32 s0, s58, 0x2400
	s_addc_u32 s1, s59, 0
	v_writelane_b32 v255, s0, 22
	s_movk_i32 s3, 0x1e20
	s_movk_i32 s94, 0x1000
	v_writelane_b32 v255, s1, 23
	s_add_u32 s0, s58, 0x3400
	s_addc_u32 s1, s59, 0
	v_writelane_b32 v255, s0, 24
	s_mov_b32 s95, 0xbfb8aa3b
	s_mov_b32 s52, 0x800000
	v_writelane_b32 v255, s1, 25
	s_add_u32 s0, s58, 0x2600
	s_addc_u32 s1, s59, 0
	v_writelane_b32 v254, s0, 60
	s_mov_b32 s53, 0x3f317217
	s_mov_b32 s54, 0x7f800000
	v_writelane_b32 v254, s1, 61
	s_add_u32 s0, s58, 0x3600
	s_addc_u32 s1, s59, 0
	v_writelane_b32 v255, s0, 0
	s_mov_b32 s4, 0x3e3504f3
	s_movk_i32 s55, 0x800
	v_writelane_b32 v255, s1, 1
	s_add_u32 s0, s58, 0x2800
	s_addc_u32 s1, s59, 0
	v_writelane_b32 v255, s0, 2
	v_mov_b32_e32 v73, 0x42800000
	v_mov_b32_e32 v74, 0x1800
	v_writelane_b32 v255, s1, 3
	s_add_u32 s0, s58, 0x3800
	s_addc_u32 s1, s59, 0
	v_writelane_b32 v255, s0, 4
	v_mov_b32_e32 v75, 0x1600
	v_mov_b32_e32 v76, 0x3e000000
	v_writelane_b32 v255, s1, 5
	s_add_u32 s0, s58, 0x2a00
	s_addc_u32 s1, s59, 0
	v_writelane_b32 v255, s0, 6
	v_mov_b32_e32 v77, 0x41b17218
	v_mov_b32_e32 v78, 0xc00
	v_writelane_b32 v255, s1, 7
	s_add_u32 s0, s58, 0x3a00
	s_addc_u32 s1, s59, 0
	v_writelane_b32 v255, s0, 8
	v_mov_b32_e32 v79, 0xb00
	v_mov_b32_e32 v80, 0x1000
	v_writelane_b32 v255, s1, 9
	s_add_u32 s0, s58, 0x2c00
	s_addc_u32 s1, s59, 0
	v_writelane_b32 v255, s0, 10
	s_waitcnt lgkmcnt(0)
	s_barrier
	v_writelane_b32 v255, s1, 11
	s_add_u32 s0, s58, 0x3c00
	s_addc_u32 s1, s59, 0
	s_add_u32 s96, s58, 0x2e00
	s_addc_u32 s97, s59, 0
	s_add_u32 s90, s58, 0x3e00
	v_writelane_b32 v255, s0, 12
	s_addc_u32 s91, s59, 0
	s_add_i32 s5, 0, 0x10010
	v_writelane_b32 v255, s1, 13
	v_mov_b32_e32 v72, s5
	s_mov_b32 s99, -1
	s_mov_b32 s100, 0
	s_cmp_lg_u32 s28, 0x200
	s_cbranch_scc1 .Lmap_done_1
	s_movk_i32 s100, 0x140
	s_cmp_ge_u32 s2, 0x100
	s_cbranch_scc1 .Lmap_hi_1
	s_mov_b32 s99, s2
	s_cmp_lt_u32 s2, 192
	s_cbranch_scc1 .Lmap_done_1
	s_add_u32 s99, s2, 64
	s_branch .Lmap_done_1

.LBB0_1510:
	s_or_b64 exec, exec, s[0:1]
	s_setprio 0
	v_readlane_b32 s0, v255, 42
	v_readlane_b32 s1, v255, 43
	s_waitcnt lgkmcnt(0)
	v_mov_b32_e32 v0, v174
	s_and_b64 vcc, exec, s[0:1]
	s_barrier
	s_cbranch_vccnz .LBB0_1526
	v_and_b32_e32 v1, 63, v0
	v_readlane_b32 s4, v255, 26
	v_readlane_b32 s52, v254, 21
	v_lshlrev_b32_e32 v1, 2, v1
	v_readlane_b32 s8, v255, 30
	v_readlane_b32 s9, v255, 31
	v_readlane_b32 s56, v254, 25
	v_readlane_b32 s57, v254, 26
	v_readlane_b32 s58, v254, 27
	v_readlane_b32 s59, v254, 28
	v_readlane_b32 s64, v254, 33
	v_readlane_b32 s65, v254, 34
	v_readlane_b32 s5, v255, 27
	v_readlane_b32 s6, v255, 28
	v_readlane_b32 s7, v255, 29
	v_readlane_b32 s10, v255, 32
	v_readlane_b32 s11, v255, 33
	v_readlane_b32 s12, v255, 34
	v_readlane_b32 s13, v255, 35
	v_readlane_b32 s14, v255, 36
	v_readlane_b32 s15, v255, 37
	v_readlane_b32 s16, v255, 38
	v_readlane_b32 s17, v255, 39
	v_readlane_b32 s18, v255, 40
	v_readlane_b32 s19, v255, 41
	global_load_dword v13, v1, s[8:9] offset:256
	global_load_dword v70, v1, s[14:15] offset:256
	v_ashrrev_i32_e32 v1, 31, v0
	v_readlane_b32 s66, v254, 35
	v_readlane_b32 s67, v254, 36
	s_mov_b64 s[56:57], s[64:65]
	v_lshlrev_b64 v[2:3], 2, v[0:1]
	s_mov_b64 s[58:59], s[66:67]
	v_readlane_b32 s4, v254, 3
	s_waitcnt vmcnt(7)
	v_lshl_add_u64 v[4:5], s[58:59], 0, v[2:3]
	v_readlane_b32 s5, v254, 4
	v_readlane_b32 s54, v254, 23
	v_readlane_b32 s55, v254, 24
	v_readlane_b32 s62, v254, 31
	v_readlane_b32 s63, v254, 32
	global_load_dword v71, v[4:5], off offset:1024
	v_lshl_add_u64 v[4:5], s[4:5], 0, v[2:3]
	s_mov_b64 s[54:55], s[62:63]
	global_load_dword v72, v[4:5], off offset:1024
	v_lshl_add_u64 v[4:5], s[56:57], 0, v[2:3]
	global_load_dword v73, v[4:5], off offset:1024
	v_lshl_add_u64 v[4:5], s[54:55], 0, v[2:3]
	global_load_dword v74, v[4:5], off offset:1024
	v_lshl_add_u64 v[4:5], s[30:31], 0, v[2:3]
	global_load_dword v75, v[4:5], off
	global_load_dword v76, v[4:5], off offset:1280
	global_load_dword v77, v[4:5], off offset:2304
	v_lshlrev_b32_e32 v4, 3, v0
	v_ashrrev_i32_e32 v78, 4, v0
	v_and_b32_e32 v12, 0x78, v4
	s_movk_i32 s0, 0x110
	v_mul_lo_u32 v4, v78, s0
	v_lshlrev_b32_e32 v5, 1, v12
	v_add3_u32 v80, 0, v4, v5
	v_and_b32_e32 v5, 15, v0
	v_mul_u32_u24_e32 v6, 0x110, v5
	v_and_b32_e32 v4, 48, v0
	v_add3_u32 v81, 0, v6, v4
	v_lshlrev_b32_e32 v6, 8, v0
	v_and_b32_e32 v6, 0x3000, v6
	v_add_u32_e32 v9, 0, v6
	v_mbcnt_hi_u32_b32 v6, -1, v175
	v_and_b32_e32 v10, 64, v6
	v_xor_b32_e32 v7, 16, v6
	v_add_u32_e32 v10, 64, v10
	v_cmp_lt_i32_e32 vcc, v7, v10
	v_and_b32_e32 v8, 0xffffffc0, v0
	v_lshlrev_b32_e32 v5, 2, v5
	v_cndmask_b32_e32 v7, v6, v7, vcc
	v_lshlrev_b32_e32 v82, 2, v7
	v_xor_b32_e32 v7, 32, v6
	v_lshlrev_b32_e32 v8, 2, v8
	v_cmp_lt_i32_e32 vcc, v7, v10
	v_add3_u32 v85, v9, v5, v8
	v_not_b32_e32 v5, 63
	v_readlane_b32 s53, v254, 22
	v_readlane_b32 s60, v254, 29
	v_readlane_b32 s61, v254, 30
	v_cndmask_b32_e32 v6, v6, v7, vcc
	v_bitop3_b32 v5, v0, 15, v5 bitop3:0xe0
	v_mov_b32_e32 v15, 0
	v_lshlrev_b32_e32 v83, 2, v6
	v_and_b32_e32 v6, 0xffffffcf, v0
	v_or_b32_e32 v8, 16, v5
	v_or_b32_e32 v10, 32, v5
	v_or_b32_e32 v24, 48, v5
	v_readlane_b32 s52, v254, 39
	v_readlane_b32 s0, v254, 19
	v_readlane_b32 s8, v254, 7
	v_readlane_b32 s9, v254, 8
	v_readlane_b32 s10, v254, 9
	v_readlane_b32 s11, v254, 10
	v_ashrrev_i32_e32 v7, 31, v6
	v_ashrrev_i32_e32 v9, 31, v8
	v_ashrrev_i32_e32 v11, 31, v10
	v_ashrrev_i32_e32 v25, 31, v24
	v_readlane_b32 s62, v254, 49
	v_readlane_b32 s63, v254, 50
	v_mov_b32_e32 v5, v15
	v_readlane_b32 s1, v254, 20
	v_readlane_b32 s6, v254, 5
	v_readlane_b32 s7, v254, 6
	v_readlane_b32 s16, v254, 15
	v_readlane_b32 s17, v254, 16
	v_readlane_b32 s18, v254, 17
	v_readlane_b32 s19, v254, 18
	v_add_u32_e32 v16, 0x700, v0
	v_add_u32_e32 v18, 0x840, v0
	v_add_u32_e32 v20, 0x940, v0
	v_lshlrev_b32_e32 v14, 2, v12
	v_lshlrev_b64 v[6:7], 8, v[6:7]
	v_lshlrev_b64 v[8:9], 8, v[8:9]
	v_lshlrev_b64 v[10:11], 8, v[10:11]
	v_lshlrev_b64 v[32:33], 8, v[24:25]
	s_mov_b64 s[10:11], s[62:63]
	v_lshl_add_u64 v[4:5], s[0:1], 0, v[4:5]
	v_lshlrev_b64 v[34:35], 1, v[0:1]
	s_mov_b32 s8, 0x358637bd
	v_and_b32_e32 v79, 7, v78
	s_mov_b32 s5, 0
	v_ashrrev_i32_e32 v17, 31, v16
	v_ashrrev_i32_e32 v19, 31, v18
	v_ashrrev_i32_e32 v21, 31, v20
	v_lshl_add_u32 v84, v0, 2, 0
	v_lshl_add_u64 v[22:23], s[30:31], 0, v[14:15]
	v_lshl_add_u64 v[24:25], s[10:11], 0, v[14:15]
	v_lshl_add_u64 v[26:27], v[4:5], 0, v[6:7]
	v_lshl_add_u64 v[28:29], v[4:5], 0, v[8:9]
	v_lshl_add_u64 v[30:31], v[4:5], 0, v[10:11]
	v_lshl_add_u64 v[32:33], v[4:5], 0, v[32:33]
	v_lshl_add_u64 v[36:37], s[40:41], 0, v[34:35]
	v_lshl_add_u64 v[38:39], s[44:45], 0, v[34:35]
	v_lshl_add_u64 v[40:41], s[10:11], 0, v[2:3]
	v_lshl_add_u64 v[42:43], s[42:43], 0, v[34:35]
	s_movk_i32 s3, 0x3fff
	s_movk_i32 s7, 0x1e20
	s_movk_i32 s16, 0x1000
	s_movk_i32 s17, 0xf000
	s_mov_b32 s18, 0xbc800000
	s_mov_b32 s6, 0x3c800000
	s_mov_b32 s9, 0x3a27c5ac
	s_mov_b32 s19, 0x800000
	v_mov_b32_e32 v86, 0x1e20
	s_mov_b32 s20, s2
	v_readlane_b32 s12, v254, 11
	v_readlane_b32 s13, v254, 12
	v_readlane_b32 s14, v254, 13
	v_readlane_b32 s15, v254, 14
	v_readlane_b32 s53, v254, 40
	v_readlane_b32 s54, v254, 41
	v_readlane_b32 s55, v254, 42
	v_readlane_b32 s56, v254, 43
	v_readlane_b32 s57, v254, 44
	v_readlane_b32 s58, v254, 45
	v_readlane_b32 s59, v254, 46
	v_readlane_b32 s60, v254, 47
	v_readlane_b32 s61, v254, 48
	v_readlane_b32 s64, v254, 51
	v_readlane_b32 s65, v254, 52
	v_readlane_b32 s66, v254, 53
	v_readlane_b32 s67, v254, 54
	s_branch .LBB0_1513

.LBB0_1578:
	s_or_b64 exec, exec, s[0:1]
	s_setprio 0
	v_mov_b32_e32 v98, v174
	s_waitcnt lgkmcnt(0)
	v_mov_b32_e32 v0, v174
	s_barrier
	s_and_b64 vcc, exec, s[68:69]
	v_ashrrev_i32_e32 v99, 7, v0
	v_bfe_u32 v100, v0, 6, 1
	s_cbranch_vccnz .LBB0_1587
	s_cmpk_gt_i32 s2, 0x10ff
	s_cbranch_scc1 .LBB0_1586
	v_and_b32_e32 v0, 15, v98
	v_lshl_or_b32 v101, v99, 6, v0
	v_lshrrev_b32_e32 v0, 2, v98
	v_and_b32_e32 v0, 12, v0
	s_add_u32 s3, s36, 0x7c0000
	v_lshl_or_b32 v102, v100, 6, v0
	s_addc_u32 s20, s37, 0
	s_movk_i32 s21, 0x70
	v_mov_b32_e32 v65, 0
	s_mov_b64 s[0:1], 0x80
	s_mov_b64 s[4:5], 0x7c0080
	s_mov_b64 s[6:7], 0x100
	s_mov_b64 s[8:9], 0x7c0100
	s_mov_b32 s24, s2
	s_waitcnt vmcnt(0)
	s_branch .LBB0_1582

.LBB0_1587:
.LBB0_1588:
	s_ashr_i32 s3, s2, 3
	s_cmpk_gt_i32 s3, 0x21f
	s_cbranch_scc1 .LBB0_1595
	s_and_b32 s20, s2, 7
	s_ashr_i32 s21, s28, 3
	v_and_b32_e32 v0, 15, v98
	v_lshl_or_b32 v99, v99, 6, v0
	v_lshrrev_b32_e32 v0, 2, v98
	s_add_u32 s24, s36, 0x7c0000
	v_and_b32_e32 v0, 12, v0
	s_addc_u32 s25, s37, 0
	s_lshl_b32 s0, s3, 3
	v_lshl_or_b32 v98, v100, 6, v0
	s_or_b32 s26, s0, s20
	s_movk_i32 s27, 0x70
	v_mov_b32_e32 v65, 0
	s_mov_b64 s[0:1], 0x80
	s_mov_b64 s[4:5], 0x7c0080
	s_mov_b64 s[6:7], 0x100
	s_mov_b64 s[8:9], 0x7c0100
	s_waitcnt vmcnt(0)
	s_cmp_lt_u32 s2, 0x100
	s_cbranch_scc1 .Lgprio_7
	s_setprio 1
.Lgprio_7:
	s_branch .LBB0_1591
.LBB0_1590:
	v_mul_f32_e32 v60, 0xbfb8aa3b, v60
	v_exp_f32_e32 v60, v60
	v_mul_f32_e32 v56, 0xbfb8aa3b, v56
	v_mul_f32_e32 v57, 0xbfb8aa3b, v57
	v_mul_f32_e32 v58, 0xbfb8aa3b, v58
	v_add_f32_e32 v60, 1.0, v60
	v_rcp_f32_e32 v64, v60
	v_mul_f32_e32 v60, 0xbfb8aa3b, v61
	v_mul_f32_e32 v61, 0xbfb8aa3b, v62
	v_exp_f32_e32 v61, v61
	v_mul_f32_e32 v62, 0xbfb8aa3b, v63
	v_exp_f32_e32 v60, v60
	v_exp_f32_e32 v62, v62
	v_add_f32_e32 v61, 1.0, v61
	v_mul_f32_e32 v59, 0xbfb8aa3b, v59
	v_add_f32_e32 v60, 1.0, v60
	v_rcp_f32_e32 v63, v61
	v_add_f32_e32 v61, 1.0, v62
	v_exp_f32_e32 v56, v56
	v_exp_f32_e32 v57, v57
	v_exp_f32_e32 v58, v58
	v_exp_f32_e32 v59, v59
	v_rcp_f32_e32 v68, v61
	v_rcp_f32_e32 v70, v60
	v_add_f32_e32 v56, 1.0, v56
	v_add_f32_e32 v57, 1.0, v57
	v_add_f32_e32 v58, 1.0, v58
	v_add_f32_e32 v59, 1.0, v59
	v_mul_f32_e32 v52, 0xbfb8aa3b, v52
	v_mul_f32_e32 v53, 0xbfb8aa3b, v53
	v_mul_f32_e32 v54, 0xbfb8aa3b, v54
	v_mul_f32_e32 v55, 0xbfb8aa3b, v55
	v_lshl_add_u32 v66, s12, 7, v99
	v_cvt_pk_f16_f32 v69, v63, v68
	v_cvt_pk_f16_f32 v68, v64, v70
	v_rcp_f32_e32 v56, v56
	v_rcp_f32_e32 v58, v58
	v_rcp_f32_e32 v59, v59
	v_rcp_f32_e32 v64, v57
	v_exp_f32_e32 v52, v52
	v_exp_f32_e32 v53, v53
	v_exp_f32_e32 v54, v54
	v_exp_f32_e32 v55, v55
	v_ashrrev_i32_e32 v67, 31, v66
	v_lshl_or_b32 v62, s10, 7, v98
	v_mul_f32_e32 v50, 0xbfb8aa3b, v50
	v_mul_f32_e32 v51, 0xbfb8aa3b, v51
	v_lshlrev_b64 v[60:61], 13, v[66:67]
	v_ashrrev_i32_e32 v63, 31, v62
	v_exp_f32_e32 v50, v50
	v_exp_f32_e32 v51, v51
	v_lshl_add_u64 v[70:71], s[42:43], 0, v[60:61]
	v_lshlrev_b64 v[60:61], 1, v[62:63]
	v_lshl_add_u64 v[62:63], v[70:71], 0, v[60:61]
	v_cvt_pk_f16_f32 v57, v58, v59
	v_cvt_pk_f16_f32 v56, v56, v64
	v_add_f32_e32 v52, 1.0, v52
	v_add_f32_e32 v53, 1.0, v53
	v_add_f32_e32 v54, 1.0, v54
	v_add_f32_e32 v55, 1.0, v55
	v_mul_f32_e32 v48, 0xbfb8aa3b, v48
	v_mul_f32_e32 v49, 0xbfb8aa3b, v49
	s_waitcnt vmcnt(0)
	s_barrier
	global_store_dwordx2 v[62:63], v[56:57], off offset:32
	v_rcp_f32_e32 v52, v52
	v_rcp_f32_e32 v54, v54
	v_rcp_f32_e32 v55, v55
	v_rcp_f32_e32 v56, v53
	v_exp_f32_e32 v48, v48
	v_exp_f32_e32 v49, v49
	v_add_f32_e32 v50, 1.0, v50
	v_add_f32_e32 v51, 1.0, v51
	v_rcp_f32_e32 v50, v50
	v_rcp_f32_e32 v51, v51
	v_cvt_pk_f16_f32 v53, v54, v55
	v_cvt_pk_f16_f32 v52, v52, v56
	v_add_f32_e32 v48, 1.0, v48
	v_add_f32_e32 v49, 1.0, v49
	global_store_dwordx2 v[62:63], v[52:53], off offset:64
	v_rcp_f32_e32 v48, v48
	v_rcp_f32_e32 v52, v49
	v_mul_f32_e32 v44, 0xbfb8aa3b, v44
	v_mul_f32_e32 v45, 0xbfb8aa3b, v45
	v_mul_f32_e32 v46, 0xbfb8aa3b, v46
	v_mul_f32_e32 v47, 0xbfb8aa3b, v47
	v_cvt_pk_f16_f32 v49, v50, v51
	v_exp_f32_e32 v50, v44
	v_exp_f32_e32 v45, v45
	v_exp_f32_e32 v46, v46
	v_exp_f32_e32 v47, v47
	v_cvt_pk_f16_f32 v48, v48, v52
	global_store_dwordx2 v[62:63], v[48:49], off offset:96
	v_add_f32_e32 v48, 1.0, v50
	v_add_f32_e32 v45, 1.0, v45
	v_add_f32_e32 v46, 1.0, v46
	v_add_f32_e32 v47, 1.0, v47
	v_mul_f32_e32 v40, 0xbfb8aa3b, v40
	v_mul_f32_e32 v41, 0xbfb8aa3b, v41
	v_mul_f32_e32 v42, 0xbfb8aa3b, v42
	v_mul_f32_e32 v43, 0xbfb8aa3b, v43
	v_or_b32_e32 v44, 16, v66
	v_rcp_f32_e32 v48, v48
	v_rcp_f32_e32 v46, v46
	v_rcp_f32_e32 v47, v47
	v_rcp_f32_e32 v49, v45
	v_exp_f32_e32 v40, v40
	v_exp_f32_e32 v41, v41
	v_exp_f32_e32 v42, v42
	v_exp_f32_e32 v43, v43
	v_ashrrev_i32_e32 v45, 31, v44
	v_lshlrev_b64 v[44:45], 13, v[44:45]
	v_lshl_add_u64 v[44:45], s[42:43], 0, v[44:45]
	v_cvt_pk_f16_f32 v47, v46, v47
	v_cvt_pk_f16_f32 v46, v48, v49
	v_lshl_add_u64 v[44:45], v[44:45], 0, v[60:61]
	v_add_f32_e32 v40, 1.0, v40
	v_add_f32_e32 v41, 1.0, v41
	v_add_f32_e32 v42, 1.0, v42
	v_add_f32_e32 v43, 1.0, v43
	v_mul_f32_e32 v36, 0xbfb8aa3b, v36
	v_mul_f32_e32 v37, 0xbfb8aa3b, v37
	v_mul_f32_e32 v38, 0xbfb8aa3b, v38
	v_mul_f32_e32 v39, 0xbfb8aa3b, v39
	global_store_dwordx2 v[44:45], v[46:47], off
	v_rcp_f32_e32 v40, v40
	v_rcp_f32_e32 v42, v42
	v_rcp_f32_e32 v43, v43
	v_rcp_f32_e32 v46, v41
	v_exp_f32_e32 v36, v36
	v_exp_f32_e32 v37, v37
	v_exp_f32_e32 v38, v38
	v_exp_f32_e32 v39, v39
	v_mul_f32_e32 v34, 0xbfb8aa3b, v34
	v_mul_f32_e32 v35, 0xbfb8aa3b, v35
	v_exp_f32_e32 v34, v34
	v_exp_f32_e32 v35, v35
	v_cvt_pk_f16_f32 v41, v42, v43
	v_cvt_pk_f16_f32 v40, v40, v46
	v_add_f32_e32 v36, 1.0, v36
	v_add_f32_e32 v37, 1.0, v37
	v_add_f32_e32 v38, 1.0, v38
	v_add_f32_e32 v39, 1.0, v39
	v_mul_f32_e32 v32, 0xbfb8aa3b, v32
	v_mul_f32_e32 v33, 0xbfb8aa3b, v33
	global_store_dwordx2 v[44:45], v[40:41], off offset:32
	v_rcp_f32_e32 v36, v36
	v_rcp_f32_e32 v38, v38
	v_rcp_f32_e32 v39, v39
	v_rcp_f32_e32 v40, v37
	v_exp_f32_e32 v32, v32
	v_exp_f32_e32 v33, v33
	v_add_f32_e32 v34, 1.0, v34
	v_add_f32_e32 v35, 1.0, v35
	v_rcp_f32_e32 v34, v34
	v_rcp_f32_e32 v35, v35
	v_cvt_pk_f16_f32 v37, v38, v39
	v_cvt_pk_f16_f32 v36, v36, v40
	v_add_f32_e32 v32, 1.0, v32
	v_add_f32_e32 v33, 1.0, v33
	global_store_dwordx2 v[44:45], v[36:37], off offset:64
	v_rcp_f32_e32 v32, v32
	v_rcp_f32_e32 v36, v33
	v_mul_f32_e32 v28, 0xbfb8aa3b, v28
	v_mul_f32_e32 v29, 0xbfb8aa3b, v29
	v_mul_f32_e32 v30, 0xbfb8aa3b, v30
	v_mul_f32_e32 v31, 0xbfb8aa3b, v31
	v_cvt_pk_f16_f32 v33, v34, v35
	v_exp_f32_e32 v34, v28
	v_exp_f32_e32 v29, v29
	v_exp_f32_e32 v30, v30
	v_exp_f32_e32 v31, v31
	v_cvt_pk_f16_f32 v32, v32, v36
	global_store_dwordx2 v[44:45], v[32:33], off offset:96
	v_add_f32_e32 v32, 1.0, v34
	v_add_f32_e32 v29, 1.0, v29
	v_add_f32_e32 v30, 1.0, v30
	v_add_f32_e32 v31, 1.0, v31
	v_mul_f32_e32 v24, 0xbfb8aa3b, v24
	v_mul_f32_e32 v25, 0xbfb8aa3b, v25
	v_mul_f32_e32 v26, 0xbfb8aa3b, v26
	v_mul_f32_e32 v27, 0xbfb8aa3b, v27
	v_or_b32_e32 v28, 32, v66
	v_rcp_f32_e32 v32, v32
	v_rcp_f32_e32 v30, v30
	v_rcp_f32_e32 v31, v31
	v_rcp_f32_e32 v33, v29
	v_exp_f32_e32 v24, v24
	v_exp_f32_e32 v25, v25
	v_exp_f32_e32 v26, v26
	v_exp_f32_e32 v27, v27
	v_ashrrev_i32_e32 v29, 31, v28
	v_lshlrev_b64 v[28:29], 13, v[28:29]
	v_lshl_add_u64 v[28:29], s[42:43], 0, v[28:29]
	v_cvt_pk_f16_f32 v31, v30, v31
	v_cvt_pk_f16_f32 v30, v32, v33
	v_lshl_add_u64 v[28:29], v[28:29], 0, v[60:61]
	v_add_f32_e32 v24, 1.0, v24
	v_add_f32_e32 v25, 1.0, v25
	v_add_f32_e32 v26, 1.0, v26
	v_add_f32_e32 v27, 1.0, v27
	v_mul_f32_e32 v20, 0xbfb8aa3b, v20
	v_mul_f32_e32 v21, 0xbfb8aa3b, v21
	v_mul_f32_e32 v22, 0xbfb8aa3b, v22
	v_mul_f32_e32 v23, 0xbfb8aa3b, v23
	global_store_dwordx2 v[28:29], v[30:31], off
	v_rcp_f32_e32 v24, v24
	v_rcp_f32_e32 v26, v26
	v_rcp_f32_e32 v27, v27
	v_rcp_f32_e32 v30, v25
	v_exp_f32_e32 v20, v20
	v_exp_f32_e32 v21, v21
	v_exp_f32_e32 v22, v22
	v_exp_f32_e32 v23, v23
	v_mul_f32_e32 v18, 0xbfb8aa3b, v18
	v_mul_f32_e32 v19, 0xbfb8aa3b, v19
	v_exp_f32_e32 v18, v18
	v_exp_f32_e32 v19, v19
	v_cvt_pk_f16_f32 v25, v26, v27
	v_cvt_pk_f16_f32 v24, v24, v30
	v_add_f32_e32 v20, 1.0, v20
	v_add_f32_e32 v21, 1.0, v21
	v_add_f32_e32 v22, 1.0, v22
	v_add_f32_e32 v23, 1.0, v23
	v_mul_f32_e32 v16, 0xbfb8aa3b, v16
	v_mul_f32_e32 v17, 0xbfb8aa3b, v17
	global_store_dwordx2 v[28:29], v[24:25], off offset:32
	v_rcp_f32_e32 v20, v20
	v_rcp_f32_e32 v22, v22
	v_rcp_f32_e32 v23, v23
	v_rcp_f32_e32 v24, v21
	v_exp_f32_e32 v16, v16
	v_exp_f32_e32 v17, v17
	v_add_f32_e32 v18, 1.0, v18
	v_add_f32_e32 v19, 1.0, v19
	v_rcp_f32_e32 v18, v18
	v_rcp_f32_e32 v19, v19
	v_cvt_pk_f16_f32 v21, v22, v23
	v_cvt_pk_f16_f32 v20, v20, v24
	v_add_f32_e32 v16, 1.0, v16
	v_add_f32_e32 v17, 1.0, v17
	global_store_dwordx2 v[28:29], v[20:21], off offset:64
	v_rcp_f32_e32 v16, v16
	v_rcp_f32_e32 v20, v17
	v_mul_f32_e32 v12, 0xbfb8aa3b, v12
	v_mul_f32_e32 v13, 0xbfb8aa3b, v13
	v_mul_f32_e32 v14, 0xbfb8aa3b, v14
	v_mul_f32_e32 v15, 0xbfb8aa3b, v15
	v_cvt_pk_f16_f32 v17, v18, v19
	v_exp_f32_e32 v18, v12
	v_exp_f32_e32 v13, v13
	v_exp_f32_e32 v14, v14
	v_exp_f32_e32 v15, v15
	v_cvt_pk_f16_f32 v16, v16, v20
	global_store_dwordx2 v[28:29], v[16:17], off offset:96
	v_add_f32_e32 v16, 1.0, v18
	v_add_f32_e32 v13, 1.0, v13
	v_add_f32_e32 v14, 1.0, v14
	v_add_f32_e32 v15, 1.0, v15
	v_mul_f32_e32 v8, 0xbfb8aa3b, v8
	v_mul_f32_e32 v9, 0xbfb8aa3b, v9
	v_mul_f32_e32 v10, 0xbfb8aa3b, v10
	v_mul_f32_e32 v11, 0xbfb8aa3b, v11
	v_or_b32_e32 v12, 48, v66
	v_rcp_f32_e32 v16, v16
	v_rcp_f32_e32 v14, v14
	v_rcp_f32_e32 v15, v15
	v_rcp_f32_e32 v17, v13
	v_exp_f32_e32 v8, v8
	v_exp_f32_e32 v9, v9
	v_exp_f32_e32 v10, v10
	v_exp_f32_e32 v11, v11
	v_mul_f32_e32 v6, 0xbfb8aa3b, v6
	v_mul_f32_e32 v7, 0xbfb8aa3b, v7
	v_ashrrev_i32_e32 v13, 31, v12
	v_exp_f32_e32 v6, v6
	v_exp_f32_e32 v7, v7
	v_lshlrev_b64 v[12:13], 13, v[12:13]
	v_lshl_add_u64 v[12:13], s[42:43], 0, v[12:13]
	v_cvt_pk_f16_f32 v15, v14, v15
	v_cvt_pk_f16_f32 v14, v16, v17
	v_lshl_add_u64 v[12:13], v[12:13], 0, v[60:61]
	v_add_f32_e32 v8, 1.0, v8
	v_add_f32_e32 v9, 1.0, v9
	v_add_f32_e32 v10, 1.0, v10
	v_add_f32_e32 v11, 1.0, v11
	v_mul_f32_e32 v4, 0xbfb8aa3b, v4
	v_mul_f32_e32 v5, 0xbfb8aa3b, v5
	v_mul_f32_e32 v0, 0xbfb8aa3b, v0
	v_mul_f32_e32 v1, 0xbfb8aa3b, v1
	v_mul_f32_e32 v2, 0xbfb8aa3b, v2
	v_mul_f32_e32 v3, 0xbfb8aa3b, v3
	global_store_dwordx2 v[12:13], v[14:15], off
	v_rcp_f32_e32 v8, v8
	v_rcp_f32_e32 v10, v10
	v_rcp_f32_e32 v11, v11
	v_rcp_f32_e32 v14, v9
	v_exp_f32_e32 v4, v4
	v_exp_f32_e32 v5, v5
	v_add_f32_e32 v6, 1.0, v6
	v_add_f32_e32 v7, 1.0, v7
	v_exp_f32_e32 v0, v0
	v_exp_f32_e32 v1, v1
	v_exp_f32_e32 v2, v2
	v_exp_f32_e32 v3, v3
	v_rcp_f32_e32 v6, v6
	v_rcp_f32_e32 v7, v7
	v_cvt_pk_f16_f32 v9, v10, v11
	v_cvt_pk_f16_f32 v8, v8, v14
	v_add_f32_e32 v4, 1.0, v4
	v_add_f32_e32 v5, 1.0, v5
	v_add_f32_e32 v0, 1.0, v0
	v_add_f32_e32 v1, 1.0, v1
	v_add_f32_e32 v2, 1.0, v2
	v_add_f32_e32 v3, 1.0, v3
	global_store_dwordx2 v[12:13], v[8:9], off offset:32
	v_rcp_f32_e32 v4, v4
	v_rcp_f32_e32 v8, v5
	v_cvt_pk_f16_f32 v5, v6, v7
	v_rcp_f32_e32 v0, v0
	v_rcp_f32_e32 v2, v2
	v_rcp_f32_e32 v3, v3
	v_rcp_f32_e32 v6, v1
	s_add_i32 s3, s3, s21
	s_add_i32 s26, s26, s28
	v_cvt_pk_f16_f32 v4, v4, v8
	v_cvt_pk_f16_f32 v1, v2, v3
	v_cvt_pk_f16_f32 v0, v0, v6
	s_cmpk_gt_i32 s3, 0x21f
	global_store_dwordx2 v[62:63], v[68:69], off
	global_store_dwordx2 v[12:13], v[4:5], off offset:64
	global_store_dwordx2 v[12:13], v[0:1], off offset:96
	s_cbranch_scc1 .LBB0_1595

.LBB0_1647:
	s_or_b64 exec, exec, s[0:1]
	s_setprio 0
	v_mov_b32_e32 v176, v174
	s_waitcnt lgkmcnt(0)
	v_mov_b32_e32 v0, v174
	s_barrier
	s_and_b64 vcc, exec, s[68:69]
	v_ashrrev_i32_e32 v177, 7, v0
	v_bfe_u32 v178, v0, 6, 1
	s_cbranch_vccnz .LBB0_1658
	s_and_b64 vcc, exec, s[30:31]
	s_cbranch_vccnz .LBB0_1657
	v_and_b32_e32 v0, 15, v176
	v_lshl_or_b32 v179, v177, 6, v0
	v_lshrrev_b32_e32 v0, 2, v176
	v_and_b32_e32 v0, 12, v0
	s_add_u32 s3, s36, 0xfc0000
	v_lshl_or_b32 v180, v178, 6, v0
	s_addc_u32 s26, s37, 0
	s_movk_i32 s27, 0x70
	s_mov_b32 s1, 0
	v_mov_b32_e32 v1, 0
	s_mov_b64 s[4:5], 0x20000
	s_mov_b64 s[6:7], 0x40000
	s_mov_b64 s[8:9], 0x60000
	s_mov_b64 s[10:11], 0x80
	s_mov_b64 s[12:13], 0xfc0080
	s_mov_b64 s[16:17], 0x100
	s_mov_b64 s[18:19], 0xfc0100
	s_mov_b32 s34, s2
	s_branch .LBB0_1651

.LBB0_1658:
.LBB0_1659:
	s_ashr_i32 s3, s2, 3
	s_cmpk_gt_i32 s3, 0x87
	s_cbranch_scc1 .LBB0_1668
	s_and_b32 s26, s2, 7
	s_ashr_i32 s27, s28, 3
	v_and_b32_e32 v0, 15, v176
	v_lshl_or_b32 v177, v177, 6, v0
	v_lshrrev_b32_e32 v0, 2, v176
	s_add_u32 s34, s36, 0xfc0000
	v_and_b32_e32 v0, 12, v0
	s_addc_u32 s35, s37, 0
	s_lshl_b32 s0, s3, 3
	v_lshl_or_b32 v176, v178, 6, v0
	s_or_b32 s44, s0, s26
	s_movk_i32 s45, 0x70
	s_mov_b32 s1, 0
	v_mov_b32_e32 v1, 0
	s_mov_b64 s[4:5], 0x20000
	s_mov_b64 s[6:7], 0x40000
	s_mov_b64 s[8:9], 0x60000
	s_mov_b64 s[10:11], 0x80
	s_mov_b64 s[12:13], 0xfc0080
	s_mov_b64 s[16:17], 0x100
	s_mov_b64 s[18:19], 0xfc0100
	s_cmp_lt_u32 s2, 0x100
	s_cbranch_scc1 .Lgprio_8
	s_setprio 1
.Lgprio_8:
	s_branch .LBB0_1662
.LBB0_1661:
	v_lshlrev_b64 v[2:3], 11, v[132:133]
	v_cvt_pk_f16_f32 v67, v66, v67
	v_cvt_pk_f16_f32 v66, v64, v65
	v_lshl_add_u64 v[2:3], s[38:39], 0, v[2:3]
	v_lshlrev_b64 v[64:65], 1, v[134:135]
	v_lshl_add_u64 v[2:3], v[2:3], 0, v[64:65]
	v_cvt_pk_f16_f32 v63, v62, v63
	v_cvt_pk_f16_f32 v62, v60, v61
	v_cvt_pk_f16_f32 v59, v58, v59
	v_cvt_pk_f16_f32 v58, v56, v57
	v_cvt_pk_f16_f32 v55, v54, v55
	v_cvt_pk_f16_f32 v54, v52, v53
	s_waitcnt vmcnt(0)
	s_barrier
	global_store_dwordx2 v[2:3], v[66:67], off
	global_store_dwordx2 v[2:3], v[62:63], off offset:32
	global_store_dwordx2 v[2:3], v[58:59], off offset:64
	global_store_dwordx2 v[2:3], v[54:55], off offset:96
	v_or_b32_e32 v2, 16, v132
	v_ashrrev_i32_e32 v3, 31, v2
	v_lshlrev_b64 v[2:3], 11, v[2:3]
	v_lshl_add_u64 v[2:3], s[38:39], 0, v[2:3]
	v_cvt_pk_f16_f32 v51, v50, v51
	v_cvt_pk_f16_f32 v50, v48, v49
	v_lshl_add_u64 v[2:3], v[2:3], 0, v[64:65]
	v_cvt_pk_f16_f32 v47, v46, v47
	v_cvt_pk_f16_f32 v46, v44, v45
	v_cvt_pk_f16_f32 v43, v42, v43
	v_cvt_pk_f16_f32 v42, v40, v41
	v_cvt_pk_f16_f32 v39, v38, v39
	v_cvt_pk_f16_f32 v38, v36, v37
	global_store_dwordx2 v[2:3], v[50:51], off
	global_store_dwordx2 v[2:3], v[46:47], off offset:32
	global_store_dwordx2 v[2:3], v[42:43], off offset:64
	global_store_dwordx2 v[2:3], v[38:39], off offset:96
	v_or_b32_e32 v2, 32, v132
	v_ashrrev_i32_e32 v3, 31, v2
	v_lshlrev_b64 v[2:3], 11, v[2:3]
	v_lshl_add_u64 v[2:3], s[38:39], 0, v[2:3]
	v_cvt_pk_f16_f32 v35, v34, v35
	v_cvt_pk_f16_f32 v34, v32, v33
	v_lshl_add_u64 v[2:3], v[2:3], 0, v[64:65]
	v_cvt_pk_f16_f32 v31, v30, v31
	v_cvt_pk_f16_f32 v30, v28, v29
	v_cvt_pk_f16_f32 v27, v26, v27
	v_cvt_pk_f16_f32 v26, v24, v25
	v_cvt_pk_f16_f32 v23, v22, v23
	v_cvt_pk_f16_f32 v22, v20, v21
	global_store_dwordx2 v[2:3], v[34:35], off
	global_store_dwordx2 v[2:3], v[30:31], off offset:32
	global_store_dwordx2 v[2:3], v[26:27], off offset:64
	global_store_dwordx2 v[2:3], v[22:23], off offset:96
	v_or_b32_e32 v2, 48, v132
	v_ashrrev_i32_e32 v3, 31, v2
	v_lshlrev_b64 v[2:3], 11, v[2:3]
	v_lshl_add_u64 v[2:3], s[38:39], 0, v[2:3]
	s_add_i32 s3, s3, s27
	s_add_i32 s44, s44, s28
	v_cvt_pk_f16_f32 v19, v18, v19
	v_cvt_pk_f16_f32 v18, v16, v17
	v_lshl_add_u64 v[2:3], v[2:3], 0, v[64:65]
	v_cvt_pk_f16_f32 v15, v14, v15
	v_cvt_pk_f16_f32 v14, v12, v13
	v_cvt_pk_f16_f32 v11, v10, v11
	v_cvt_pk_f16_f32 v10, v8, v9
	v_cvt_pk_f16_f32 v7, v6, v7
	v_cvt_pk_f16_f32 v6, v4, v5
	s_cmpk_gt_i32 s3, 0x87
	global_store_dwordx2 v[2:3], v[18:19], off
	global_store_dwordx2 v[2:3], v[14:15], off offset:32
	global_store_dwordx2 v[2:3], v[10:11], off offset:64
	global_store_dwordx2 v[2:3], v[6:7], off offset:96
	s_cbranch_scc1 .LBB0_1668

.LBB0_1720:
	s_or_b64 exec, exec, s[0:1]
	s_setprio 0
	v_mov_b32_e32 v98, v174
	s_waitcnt lgkmcnt(0)
	v_mov_b32_e32 v0, v174
	s_barrier
	s_and_b64 vcc, exec, s[68:69]
	v_ashrrev_i32_e32 v99, 7, v0
	v_bfe_u32 v100, v0, 6, 1
	s_cbranch_vccnz .LBB0_1729
	s_and_b64 vcc, exec, s[30:31]
	s_cbranch_vccnz .LBB0_1728
	v_and_b32_e32 v0, 15, v98
	v_lshl_or_b32 v101, v99, 6, v0
	v_lshrrev_b32_e32 v0, 2, v98
	v_and_b32_e32 v0, 12, v0
	v_lshl_or_b32 v102, v100, 6, v0
	s_movk_i32 s3, 0x70
	v_mov_b32_e32 v65, 0
	s_mov_b64 s[0:1], 0x80
	s_mov_b64 s[4:5], 0x11c0080
	s_mov_b64 s[6:7], 0x100
	s_mov_b64 s[8:9], 0x11c0100
	s_mov_b32 s20, s2
	s_branch .LBB0_1724

.LBB0_1729:
.LBB0_1730:
	s_ashr_i32 s3, s2, 3
	s_cmpk_gt_i32 s3, 0x87
	s_cbranch_scc1 .LBB0_1737
	v_and_b32_e32 v0, 15, v98
	v_lshl_or_b32 v99, v99, 6, v0
	v_lshrrev_b32_e32 v0, 2, v98
	s_and_b32 s20, s2, 7
	v_and_b32_e32 v0, 12, v0
	s_lshl_b32 s0, s3, 3
	s_ashr_i32 s21, s28, 3
	v_lshl_or_b32 v98, v100, 6, v0
	s_or_b32 s24, s0, s20
	s_movk_i32 s25, 0x70
	v_mov_b32_e32 v65, 0
	s_mov_b64 s[0:1], 0x80
	s_mov_b64 s[4:5], 0x11c0080
	s_mov_b64 s[6:7], 0x100
	s_mov_b64 s[8:9], 0x11c0100
	s_cmp_lt_u32 s2, 0x100
	s_cbranch_scc1 .Lgprio_9
	s_setprio 1
.Lgprio_9:
	s_branch .LBB0_1733
.LBB0_1732:
	v_lshl_add_u32 v116, s12, 7, v99
	v_ashrrev_i32_e32 v117, 31, v116
	v_readlane_b32 s52, v254, 3
	v_lshlrev_b64 v[66:67], 12, v[116:117]
	v_readlane_b32 s53, v254, 4
	v_readlane_b32 s54, v254, 5
	v_readlane_b32 s55, v254, 6
	v_readlane_b32 s64, v254, 15
	v_readlane_b32 s65, v254, 16
	v_or_b32_e32 v82, 16, v116
	v_or_b32_e32 v100, 32, v116
	v_or_b32_e32 v116, 48, v116
	v_readlane_b32 s66, v254, 17
	v_readlane_b32 s67, v254, 18
	s_mov_b64 s[52:53], s[64:65]
	v_lshl_or_b32 v68, s10, 7, v98
	v_ashrrev_i32_e32 v83, 31, v82
	v_ashrrev_i32_e32 v101, 31, v100
	v_ashrrev_i32_e32 v117, 31, v116
	s_mov_b64 s[54:55], s[66:67]
	v_ashrrev_i32_e32 v69, 31, v68
	v_lshlrev_b64 v[82:83], 12, v[82:83]
	v_lshlrev_b64 v[100:101], 12, v[100:101]
	v_lshlrev_b64 v[116:117], 12, v[116:117]
	v_lshl_add_u64 v[66:67], s[54:55], 0, v[66:67]
	v_lshlrev_b64 v[118:119], 2, v[68:69]
	v_lshl_add_u64 v[82:83], s[54:55], 0, v[82:83]
	v_lshl_add_u64 v[100:101], s[54:55], 0, v[100:101]
	v_lshl_add_u64 v[116:117], s[54:55], 0, v[116:117]
	v_lshl_add_u64 v[132:133], v[66:67], 0, v[118:119]
	v_lshl_add_u64 v[134:135], v[82:83], 0, v[118:119]
	v_lshl_add_u64 v[136:137], v[100:101], 0, v[118:119]
	v_lshl_add_u64 v[138:139], v[116:117], 0, v[118:119]
	s_waitcnt vmcnt(0)
	s_barrier
	global_load_dwordx4 v[66:69], v[132:133], off
	global_load_dwordx4 v[70:73], v[132:133], off offset:64
	global_load_dwordx4 v[74:77], v[132:133], off offset:128
	global_load_dwordx4 v[78:81], v[132:133], off offset:192
	global_load_dwordx4 v[82:85], v[134:135], off
	global_load_dwordx4 v[86:89], v[134:135], off offset:64
	global_load_dwordx4 v[90:93], v[134:135], off offset:128
	global_load_dwordx4 v[94:97], v[134:135], off offset:192
	global_load_dwordx4 v[100:103], v[136:137], off
	global_load_dwordx4 v[104:107], v[136:137], off offset:64
	global_load_dwordx4 v[108:111], v[136:137], off offset:128
	global_load_dwordx4 v[112:115], v[136:137], off offset:192
	global_load_dwordx4 v[116:119], v[138:139], off
	global_load_dwordx4 v[120:123], v[138:139], off offset:64
	global_load_dwordx4 v[124:127], v[138:139], off offset:128
	global_load_dwordx4 v[128:131], v[138:139], off offset:192
	s_add_i32 s3, s3, s21
	s_add_i32 s24, s24, s28
	s_cmpk_gt_i32 s3, 0x87
	v_readlane_b32 s56, v254, 7
	v_readlane_b32 s57, v254, 8
	v_readlane_b32 s58, v254, 9
	v_readlane_b32 s59, v254, 10
	v_readlane_b32 s60, v254, 11
	v_readlane_b32 s61, v254, 12
	v_readlane_b32 s62, v254, 13
	v_readlane_b32 s63, v254, 14
	s_waitcnt vmcnt(15)
	v_pk_add_f32 v[60:61], v[60:61], v[66:67]
	v_pk_add_f32 v[62:63], v[62:63], v[68:69]
	s_waitcnt vmcnt(11)
	v_pk_add_f32 v[44:45], v[44:45], v[82:83]
	v_pk_add_f32 v[46:47], v[46:47], v[84:85]
	v_pk_add_f32 v[56:57], v[56:57], v[70:71]
	v_pk_add_f32 v[58:59], v[58:59], v[72:73]
	s_waitcnt vmcnt(0)
	v_pk_add_f32 v[0:1], v[0:1], v[128:129]
	v_pk_add_f32 v[2:3], v[2:3], v[130:131]
	v_pk_add_f32 v[52:53], v[52:53], v[74:75]
	v_pk_add_f32 v[54:55], v[54:55], v[76:77]
	v_pk_add_f32 v[48:49], v[48:49], v[78:79]
	v_pk_add_f32 v[50:51], v[50:51], v[80:81]
	global_store_dwordx4 v[132:133], v[60:63], off
	global_store_dwordx4 v[132:133], v[56:59], off offset:64
	global_store_dwordx4 v[132:133], v[52:55], off offset:128
	global_store_dwordx4 v[132:133], v[48:51], off offset:192
	v_pk_add_f32 v[40:41], v[40:41], v[86:87]
	v_pk_add_f32 v[42:43], v[42:43], v[88:89]
	v_pk_add_f32 v[36:37], v[36:37], v[90:91]
	v_pk_add_f32 v[38:39], v[38:39], v[92:93]
	v_pk_add_f32 v[32:33], v[32:33], v[94:95]
	v_pk_add_f32 v[34:35], v[34:35], v[96:97]
	v_pk_add_f32 v[28:29], v[28:29], v[100:101]
	v_pk_add_f32 v[30:31], v[30:31], v[102:103]
	v_pk_add_f32 v[24:25], v[24:25], v[104:105]
	v_pk_add_f32 v[26:27], v[26:27], v[106:107]
	v_pk_add_f32 v[20:21], v[20:21], v[108:109]
	v_pk_add_f32 v[22:23], v[22:23], v[110:111]
	v_pk_add_f32 v[16:17], v[16:17], v[112:113]
	v_pk_add_f32 v[18:19], v[18:19], v[114:115]
	v_pk_add_f32 v[12:13], v[12:13], v[116:117]
	v_pk_add_f32 v[14:15], v[14:15], v[118:119]
	v_pk_add_f32 v[8:9], v[8:9], v[120:121]
	v_pk_add_f32 v[10:11], v[10:11], v[122:123]
	v_pk_add_f32 v[4:5], v[4:5], v[124:125]
	v_pk_add_f32 v[6:7], v[6:7], v[126:127]
	global_store_dwordx4 v[134:135], v[44:47], off
	global_store_dwordx4 v[134:135], v[40:43], off offset:64
	global_store_dwordx4 v[134:135], v[36:39], off offset:128
	global_store_dwordx4 v[134:135], v[32:35], off offset:192
	global_store_dwordx4 v[136:137], v[28:31], off
	global_store_dwordx4 v[136:137], v[24:27], off offset:64
	global_store_dwordx4 v[136:137], v[20:23], off offset:128
	global_store_dwordx4 v[136:137], v[16:19], off offset:192
	global_store_dwordx4 v[138:139], v[12:15], off
	global_store_dwordx4 v[138:139], v[8:11], off offset:64
	global_store_dwordx4 v[138:139], v[4:7], off offset:128
	global_store_dwordx4 v[138:139], v[0:3], off offset:192
	s_cbranch_scc1 .LBB0_1737

.LBB0_1789:
	s_or_b64 exec, exec, s[0:1]
	s_setprio 0
	s_waitcnt lgkmcnt(0)
	v_mov_b32_e32 v0, v174
	v_mov_b32_e32 v1, v174
	s_barrier
	v_readlane_b32 s0, v254, 55
	v_ashrrev_i32_e32 v1, 6, v1
	s_movk_i32 s3, 0x4400
	v_add_u32_e32 v50, s0, v1
	v_cmp_gt_i32_e32 vcc, s3, v50
	s_and_saveexec_b64 s[4:5], vcc
	s_cbranch_execz .LBB0_1800
	v_lshlrev_b32_e32 v0, 2, v0
	v_and_b32_e32 v0, 0xfc, v0
	v_readlane_b32 s12, v254, 3
	v_mov_b32_e32 v41, 0
	v_lshlrev_b32_e32 v40, 2, v0
	v_readlane_b32 s18, v254, 9
	v_readlane_b32 s19, v254, 10
	s_mov_b64 s[0:1], 0x1000
	v_mbcnt_hi_u32_b32 v1, -1, v175
	v_lshl_add_u64 v[2:3], s[18:19], 0, v[40:41]
	v_lshl_add_u64 v[42:43], v[2:3], 0, s[0:1]
	v_and_b32_e32 v3, 64, v1
	v_xor_b32_e32 v2, 16, v1
	v_add_u32_e32 v3, 64, v3
	v_cmp_lt_i32_e32 vcc, v2, v3
	v_readlane_b32 s13, v254, 4
	v_lshlrev_b32_e32 v40, 1, v0
	v_cndmask_b32_e32 v2, v1, v2, vcc
	v_lshlrev_b32_e32 v47, 2, v2
	v_xor_b32_e32 v2, 32, v1
	v_cmp_lt_i32_e32 vcc, v2, v3
	s_lshl_b32 s11, s28, 2
	v_lshl_add_u64 v[44:45], s[38:39], 0, v[40:41]
	v_cndmask_b32_e32 v1, v1, v2, vcc
	v_lshlrev_b32_e32 v62, 2, v1
	s_mov_b64 s[8:9], 0
	s_movk_i32 s12, 0x43ff
	v_lshlrev_b32_e32 v40, 2, v0
	s_mov_b32 s10, 0x3a800000
	v_mov_b32_e32 v46, 0x358637bd
	s_mov_b32 s13, 0x800000
	v_readlane_b32 s14, v254, 5
	v_readlane_b32 s15, v254, 6
	v_readlane_b32 s16, v254, 7
	v_readlane_b32 s17, v254, 8
	v_readlane_b32 s20, v254, 11
	v_readlane_b32 s21, v254, 12
	v_readlane_b32 s22, v254, 13
	v_readlane_b32 s23, v254, 14
	v_readlane_b32 s24, v254, 15
	v_readlane_b32 s25, v254, 16
	v_readlane_b32 s26, v254, 17
	v_readlane_b32 s27, v254, 18
	s_branch .LBB0_1792

.LBB0_1852:
	s_or_b64 exec, exec, s[0:1]
	s_setprio 0
	v_mov_b32_e32 v98, v174
	s_waitcnt lgkmcnt(0)
	v_mov_b32_e32 v0, v174
	s_barrier
	s_and_b64 vcc, exec, s[68:69]
	v_ashrrev_i32_e32 v99, 7, v0
	v_bfe_u32 v100, v0, 6, 1
	s_cbranch_vccnz .LBB0_1861
	s_cmpk_gt_i32 s2, 0x175f
	s_cbranch_scc1 .LBB0_1860
	v_and_b32_e32 v0, 15, v98
	v_lshl_or_b32 v101, v99, 6, v0
	v_lshrrev_b32_e32 v0, 2, v98
	v_and_b32_e32 v0, 12, v0
	s_add_u32 s3, s36, 0x13c0000
	v_lshl_or_b32 v102, v100, 5, v0
	s_addc_u32 s20, s37, 0
	s_movk_i32 s21, 0x70
	v_mov_b32_e32 v65, 0
	s_mov_b64 s[0:1], 0x80
	s_mov_b64 s[4:5], 0x13c0080
	s_mov_b64 s[6:7], 0x100
	s_mov_b64 s[8:9], 0x13c0100
	s_movk_i32 s22, 0x1600
	s_mov_b32 s23, s2
	s_waitcnt vmcnt(0)
	s_branch .LBB0_1856

.LBB0_1861:
.LBB0_1862:
	s_ashr_i32 s3, s2, 3
	s_cmpk_gt_i32 s3, 0x2eb
	s_cbranch_scc1 .LBB0_1869
	s_and_b32 s20, s2, 7
	s_ashr_i32 s21, s28, 3
	v_and_b32_e32 v0, 15, v98
	v_lshl_or_b32 v99, v99, 6, v0
	v_lshrrev_b32_e32 v0, 2, v98
	s_add_u32 s22, s36, 0x13c0000
	v_and_b32_e32 v0, 12, v0
	s_addc_u32 s23, s37, 0
	s_lshl_b32 s0, s3, 3
	v_lshl_or_b32 v98, v100, 5, v0
	s_or_b32 s24, s0, s20
	s_movk_i32 s25, 0x70
	v_mov_b32_e32 v65, 0
	s_mov_b64 s[0:1], 0x80
	s_mov_b64 s[4:5], 0x13c0080
	s_mov_b64 s[6:7], 0x100
	s_mov_b64 s[8:9], 0x13c0100
	s_movk_i32 s26, 0x1600
	s_waitcnt vmcnt(0)
	s_cmp_lt_u32 s2, 0x100
	s_cbranch_scc1 .Lgprio_10
	s_setprio 1
.Lgprio_10:
	s_branch .LBB0_1865
.LBB0_1864:
	v_mul_f32_e32 v64, 0xbfb8aa3b, v60
	v_exp_f32_e32 v64, v64
	v_mul_f32_e32 v66, 0xbfb8aa3b, v61
	v_exp_f32_e32 v67, v66
	v_lshl_add_u32 v70, s12, 7, v99
	v_add_f32_e32 v64, 1.0, v64
	v_rcp_f32_e32 v66, v64
	v_add_f32_e32 v64, 1.0, v67
	v_mul_f32_e32 v67, 0xbfb8aa3b, v62
	v_exp_f32_e32 v68, v67
	v_mul_f32_e32 v67, 0xbfb8aa3b, v63
	v_exp_f32_e32 v69, v67
	v_rcp_f32_e32 v67, v64
	v_add_f32_e32 v64, 1.0, v68
	v_rcp_f32_e32 v68, v64
	v_add_f32_e32 v64, 1.0, v69
	v_rcp_f32_e32 v69, v64
	v_pk_mul_f32 v[60:61], v[60:61], v[66:67]
	v_mul_f32_e32 v64, 0xbfb8aa3b, v52
	v_pk_mul_f32 v[56:57], v[56:57], v[60:61]
	v_exp_f32_e32 v64, v64
	v_cvt_pk_f16_f32 v60, v56, v57
	v_pk_mul_f32 v[56:57], v[62:63], v[68:69]
	v_mul_f32_e32 v66, 0xbfb8aa3b, v53
	v_pk_mul_f32 v[56:57], v[58:59], v[56:57]
	v_lshl_or_b32 v58, s10, 6, v98
	v_cvt_pk_f16_f32 v61, v56, v57
	v_mov_b64_e32 v[56:57], s[42:43]
	v_ashrrev_i32_e32 v59, 31, v58
	v_exp_f32_e32 v66, v66
	v_mad_i64_i32 v[62:63], s[10:11], v70, s26, v[56:57]
	v_lshlrev_b64 v[58:59], 1, v[58:59]
	v_lshl_add_u64 v[62:63], v[62:63], 0, v[58:59]
	s_waitcnt vmcnt(0)
	s_barrier
	global_store_dwordx2 v[62:63], v[60:61], off
	v_add_f32_e32 v60, 1.0, v64
	v_mul_f32_e32 v64, 0xbfb8aa3b, v54
	v_add_f32_e32 v61, 1.0, v66
	v_exp_f32_e32 v64, v64
	v_mul_f32_e32 v66, 0xbfb8aa3b, v55
	v_exp_f32_e32 v67, v66
	v_rcp_f32_e32 v60, v60
	v_add_f32_e32 v64, 1.0, v64
	v_rcp_f32_e32 v61, v61
	v_rcp_f32_e32 v66, v64
	v_add_f32_e32 v64, 1.0, v67
	v_rcp_f32_e32 v67, v64
	v_pk_mul_f32 v[52:53], v[52:53], v[60:61]
	s_add_i32 s3, s3, s21
	v_pk_mul_f32 v[48:49], v[48:49], v[52:53]
	v_pk_mul_f32 v[52:53], v[54:55], v[66:67]
	v_cvt_pk_f16_f32 v48, v48, v49
	v_pk_mul_f32 v[50:51], v[50:51], v[52:53]
	v_or_b32_e32 v52, 16, v70
	v_cvt_pk_f16_f32 v49, v50, v51
	global_store_dwordx2 v[62:63], v[48:49], off offset:32
	v_mul_f32_e32 v48, 0xbfb8aa3b, v44
	v_mul_f32_e32 v49, 0xbfb8aa3b, v45
	v_exp_f32_e32 v48, v48
	v_exp_f32_e32 v49, v49
	v_mul_f32_e32 v50, 0xbfb8aa3b, v46
	v_mul_f32_e32 v51, 0xbfb8aa3b, v47
	v_exp_f32_e32 v50, v50
	v_exp_f32_e32 v51, v51
	v_add_f32_e32 v48, 1.0, v48
	v_add_f32_e32 v49, 1.0, v49
	v_rcp_f32_e32 v48, v48
	v_rcp_f32_e32 v49, v49
	v_add_f32_e32 v50, 1.0, v50
	v_add_f32_e32 v51, 1.0, v51
	v_rcp_f32_e32 v50, v50
	v_rcp_f32_e32 v51, v51
	v_pk_mul_f32 v[44:45], v[44:45], v[48:49]
	s_add_i32 s24, s24, s28
	v_pk_mul_f32 v[40:41], v[40:41], v[44:45]
	v_pk_mul_f32 v[44:45], v[46:47], v[50:51]
	v_cvt_pk_f16_f32 v40, v40, v41
	v_pk_mul_f32 v[42:43], v[42:43], v[44:45]
	v_mul_f32_e32 v44, 0xbfb8aa3b, v36
	v_mul_f32_e32 v45, 0xbfb8aa3b, v37
	v_exp_f32_e32 v44, v44
	v_exp_f32_e32 v45, v45
	v_cvt_pk_f16_f32 v41, v42, v43
	v_mad_i64_i32 v[42:43], s[10:11], v52, s26, v[56:57]
	v_lshl_add_u64 v[42:43], v[42:43], 0, v[58:59]
	global_store_dwordx2 v[42:43], v[40:41], off
	v_add_f32_e32 v40, 1.0, v44
	v_add_f32_e32 v41, 1.0, v45
	v_mul_f32_e32 v44, 0xbfb8aa3b, v38
	v_mul_f32_e32 v45, 0xbfb8aa3b, v39
	v_exp_f32_e32 v44, v44
	v_exp_f32_e32 v45, v45
	v_rcp_f32_e32 v40, v40
	v_rcp_f32_e32 v41, v41
	v_add_f32_e32 v44, 1.0, v44
	v_add_f32_e32 v45, 1.0, v45
	v_rcp_f32_e32 v44, v44
	v_rcp_f32_e32 v45, v45
	v_pk_mul_f32 v[36:37], v[36:37], v[40:41]
	s_cmpk_gt_i32 s3, 0x2eb
	v_pk_mul_f32 v[32:33], v[32:33], v[36:37]
	v_pk_mul_f32 v[36:37], v[38:39], v[44:45]
	v_cvt_pk_f16_f32 v32, v32, v33
	v_pk_mul_f32 v[34:35], v[34:35], v[36:37]
	v_or_b32_e32 v36, 32, v70
	v_cvt_pk_f16_f32 v33, v34, v35
	global_store_dwordx2 v[42:43], v[32:33], off offset:32
	v_mul_f32_e32 v32, 0xbfb8aa3b, v28
	v_mul_f32_e32 v33, 0xbfb8aa3b, v29
	v_exp_f32_e32 v32, v32
	v_exp_f32_e32 v33, v33
	v_mul_f32_e32 v34, 0xbfb8aa3b, v30
	v_mul_f32_e32 v35, 0xbfb8aa3b, v31
	v_exp_f32_e32 v34, v34
	v_exp_f32_e32 v35, v35
	v_add_f32_e32 v32, 1.0, v32
	v_add_f32_e32 v33, 1.0, v33
	v_rcp_f32_e32 v32, v32
	v_rcp_f32_e32 v33, v33
	v_add_f32_e32 v34, 1.0, v34
	v_add_f32_e32 v35, 1.0, v35
	v_rcp_f32_e32 v34, v34
	v_rcp_f32_e32 v35, v35
	v_pk_mul_f32 v[28:29], v[28:29], v[32:33]
	s_nop 0
	v_pk_mul_f32 v[24:25], v[24:25], v[28:29]
	v_pk_mul_f32 v[28:29], v[30:31], v[34:35]
	v_cvt_pk_f16_f32 v24, v24, v25
	v_pk_mul_f32 v[26:27], v[26:27], v[28:29]
	v_mul_f32_e32 v28, 0xbfb8aa3b, v20
	v_mul_f32_e32 v29, 0xbfb8aa3b, v21
	v_exp_f32_e32 v28, v28
	v_exp_f32_e32 v29, v29
	v_cvt_pk_f16_f32 v25, v26, v27
	v_mad_i64_i32 v[26:27], s[10:11], v36, s26, v[56:57]
	v_lshl_add_u64 v[26:27], v[26:27], 0, v[58:59]
	global_store_dwordx2 v[26:27], v[24:25], off
	v_add_f32_e32 v24, 1.0, v28
	v_add_f32_e32 v25, 1.0, v29
	v_mul_f32_e32 v28, 0xbfb8aa3b, v22
	v_mul_f32_e32 v29, 0xbfb8aa3b, v23
	v_exp_f32_e32 v28, v28
	v_exp_f32_e32 v29, v29
	v_rcp_f32_e32 v24, v24
	v_rcp_f32_e32 v25, v25
	v_add_f32_e32 v28, 1.0, v28
	v_add_f32_e32 v29, 1.0, v29
	v_rcp_f32_e32 v28, v28
	v_rcp_f32_e32 v29, v29
	v_pk_mul_f32 v[20:21], v[20:21], v[24:25]
	s_nop 0
	v_pk_mul_f32 v[16:17], v[16:17], v[20:21]
	v_pk_mul_f32 v[20:21], v[22:23], v[28:29]
	v_cvt_pk_f16_f32 v16, v16, v17
	v_pk_mul_f32 v[18:19], v[18:19], v[20:21]
	v_or_b32_e32 v20, 48, v70
	v_cvt_pk_f16_f32 v17, v18, v19
	global_store_dwordx2 v[26:27], v[16:17], off offset:32
	v_mul_f32_e32 v16, 0xbfb8aa3b, v12
	v_mul_f32_e32 v17, 0xbfb8aa3b, v13
	v_exp_f32_e32 v16, v16
	v_exp_f32_e32 v17, v17
	v_mul_f32_e32 v18, 0xbfb8aa3b, v14
	v_mul_f32_e32 v19, 0xbfb8aa3b, v15
	v_exp_f32_e32 v18, v18
	v_exp_f32_e32 v19, v19
	v_add_f32_e32 v16, 1.0, v16
	v_add_f32_e32 v17, 1.0, v17
	v_rcp_f32_e32 v16, v16
	v_rcp_f32_e32 v17, v17
	v_add_f32_e32 v18, 1.0, v18
	v_add_f32_e32 v19, 1.0, v19
	v_rcp_f32_e32 v18, v18
	v_rcp_f32_e32 v19, v19
	v_pk_mul_f32 v[12:13], v[12:13], v[16:17]
	s_nop 0
	v_pk_mul_f32 v[8:9], v[8:9], v[12:13]
	v_pk_mul_f32 v[12:13], v[14:15], v[18:19]
	v_cvt_pk_f16_f32 v8, v8, v9
	v_pk_mul_f32 v[10:11], v[10:11], v[12:13]
	v_mul_f32_e32 v12, 0xbfb8aa3b, v4
	v_mul_f32_e32 v13, 0xbfb8aa3b, v5
	v_exp_f32_e32 v12, v12
	v_exp_f32_e32 v13, v13
	v_cvt_pk_f16_f32 v9, v10, v11
	v_mad_i64_i32 v[10:11], s[10:11], v20, s26, v[56:57]
	v_lshl_add_u64 v[10:11], v[10:11], 0, v[58:59]
	global_store_dwordx2 v[10:11], v[8:9], off
	v_add_f32_e32 v8, 1.0, v12
	v_add_f32_e32 v9, 1.0, v13
	v_mul_f32_e32 v12, 0xbfb8aa3b, v6
	v_mul_f32_e32 v13, 0xbfb8aa3b, v7
	v_exp_f32_e32 v12, v12
	v_exp_f32_e32 v13, v13
	v_rcp_f32_e32 v8, v8
	v_rcp_f32_e32 v9, v9
	v_add_f32_e32 v12, 1.0, v12
	v_add_f32_e32 v13, 1.0, v13
	v_rcp_f32_e32 v12, v12
	v_rcp_f32_e32 v13, v13
	v_pk_mul_f32 v[4:5], v[4:5], v[8:9]
	s_nop 0
	v_pk_mul_f32 v[0:1], v[0:1], v[4:5]
	v_pk_mul_f32 v[4:5], v[6:7], v[12:13]
	v_cvt_pk_f16_f32 v0, v0, v1
	v_pk_mul_f32 v[2:3], v[2:3], v[4:5]
	s_nop 0
	v_cvt_pk_f16_f32 v1, v2, v3
	global_store_dwordx2 v[10:11], v[0:1], off offset:32
	s_cbranch_scc1 .LBB0_1869

.LBB0_1921:
	s_or_b64 exec, exec, s[0:1]
	s_setprio 0
	v_mov_b32_e32 v98, v174
	s_waitcnt lgkmcnt(0)
	v_mov_b32_e32 v0, v174
	s_barrier
	s_and_b64 vcc, exec, s[68:69]
	v_ashrrev_i32_e32 v99, 7, v0
	v_bfe_u32 v100, v0, 6, 1
	s_cbranch_vccnz .LBB0_1930
	s_and_b64 vcc, exec, s[30:31]
	s_cbranch_vccnz .LBB0_1929
	v_and_b32_e32 v0, 15, v98
	v_lshl_or_b32 v101, v99, 6, v0
	v_lshrrev_b32_e32 v0, 2, v98
	v_and_b32_e32 v0, 12, v0
	v_lshl_or_b32 v102, v100, 6, v0
	s_movk_i32 s3, 0x1600
	s_movk_i32 s16, 0x70
	v_mov_b32_e32 v65, 0
	s_mov_b64 s[0:1], 0x80
	s_mov_b64 s[4:5], 0x1ec0080
	s_mov_b64 s[6:7], 0x100
	s_mov_b64 s[8:9], 0x1ec0100
	s_mov_b32 s17, s2
	s_branch .LBB0_1925

.LBB0_1930:
.LBB0_1931:
	s_ashr_i32 s12, s2, 3
	s_cmpk_gt_i32 s12, 0x87
	s_cbranch_scc1 .LBB0_1938
	v_and_b32_e32 v0, 15, v98
	v_lshl_or_b32 v99, v99, 6, v0
	v_lshrrev_b32_e32 v0, 2, v98
	s_and_b32 s13, s2, 7
	v_and_b32_e32 v0, 12, v0
	s_lshl_b32 s0, s12, 3
	s_ashr_i32 s16, s28, 3
	v_lshl_or_b32 v98, v100, 6, v0
	s_or_b32 s17, s0, s13
	s_movk_i32 s18, 0x1600
	s_movk_i32 s19, 0x70
	v_mov_b32_e32 v65, 0
	s_mov_b64 s[0:1], 0x80
	s_mov_b64 s[2:3], 0x1ec0080
	s_mov_b64 s[4:5], 0x100
	s_mov_b64 s[6:7], 0x1ec0100
	s_cmp_lt_u32 s2, 0x100
	s_cbranch_scc1 .Lgprio_11
	s_setprio 1
.Lgprio_11:
	s_branch .LBB0_1934
.LBB0_1933:
	v_lshl_add_u32 v116, s21, 7, v99
	v_ashrrev_i32_e32 v117, 31, v116
	v_readlane_b32 s52, v254, 3
	v_lshlrev_b64 v[66:67], 12, v[116:117]
	v_readlane_b32 s64, v254, 15
	v_readlane_b32 s65, v254, 16
	v_or_b32_e32 v82, 16, v116
	v_or_b32_e32 v100, 32, v116
	v_or_b32_e32 v116, 48, v116
	v_readlane_b32 s66, v254, 17
	v_readlane_b32 s67, v254, 18
	s_mov_b64 s[24:25], s[64:65]
	v_lshl_or_b32 v68, s20, 7, v98
	v_ashrrev_i32_e32 v83, 31, v82
	v_ashrrev_i32_e32 v101, 31, v100
	v_ashrrev_i32_e32 v117, 31, v116
	s_mov_b64 s[26:27], s[66:67]
	v_ashrrev_i32_e32 v69, 31, v68
	v_lshlrev_b64 v[82:83], 12, v[82:83]
	v_lshlrev_b64 v[100:101], 12, v[100:101]
	v_lshlrev_b64 v[116:117], 12, v[116:117]
	v_lshl_add_u64 v[66:67], s[26:27], 0, v[66:67]
	v_lshlrev_b64 v[118:119], 2, v[68:69]
	v_lshl_add_u64 v[82:83], s[26:27], 0, v[82:83]
	v_lshl_add_u64 v[100:101], s[26:27], 0, v[100:101]
	v_lshl_add_u64 v[116:117], s[26:27], 0, v[116:117]
	v_lshl_add_u64 v[132:133], v[66:67], 0, v[118:119]
	v_lshl_add_u64 v[134:135], v[82:83], 0, v[118:119]
	v_lshl_add_u64 v[136:137], v[100:101], 0, v[118:119]
	v_lshl_add_u64 v[138:139], v[116:117], 0, v[118:119]
	s_waitcnt vmcnt(0)
	s_barrier
	global_load_dwordx4 v[66:69], v[132:133], off
	global_load_dwordx4 v[70:73], v[132:133], off offset:64
	global_load_dwordx4 v[74:77], v[132:133], off offset:128
	global_load_dwordx4 v[78:81], v[132:133], off offset:192
	global_load_dwordx4 v[82:85], v[134:135], off
	global_load_dwordx4 v[86:89], v[134:135], off offset:64
	global_load_dwordx4 v[90:93], v[134:135], off offset:128
	global_load_dwordx4 v[94:97], v[134:135], off offset:192
	global_load_dwordx4 v[100:103], v[136:137], off
	global_load_dwordx4 v[104:107], v[136:137], off offset:64
	global_load_dwordx4 v[108:111], v[136:137], off offset:128
	global_load_dwordx4 v[112:115], v[136:137], off offset:192
	global_load_dwordx4 v[116:119], v[138:139], off
	global_load_dwordx4 v[120:123], v[138:139], off offset:64
	global_load_dwordx4 v[124:127], v[138:139], off offset:128
	global_load_dwordx4 v[128:131], v[138:139], off offset:192
	s_add_i32 s12, s12, s16
	s_add_i32 s17, s17, s28
	s_cmpk_gt_i32 s12, 0x87
	v_readlane_b32 s53, v254, 4
	v_readlane_b32 s54, v254, 5
	v_readlane_b32 s55, v254, 6
	v_readlane_b32 s56, v254, 7
	v_readlane_b32 s57, v254, 8
	v_readlane_b32 s58, v254, 9
	v_readlane_b32 s59, v254, 10
	v_readlane_b32 s60, v254, 11
	v_readlane_b32 s61, v254, 12
	v_readlane_b32 s62, v254, 13
	v_readlane_b32 s63, v254, 14
	s_waitcnt vmcnt(15)
	v_pk_add_f32 v[60:61], v[60:61], v[66:67]
	v_pk_add_f32 v[62:63], v[62:63], v[68:69]
	s_waitcnt vmcnt(11)
	v_pk_add_f32 v[44:45], v[44:45], v[82:83]
	v_pk_add_f32 v[46:47], v[46:47], v[84:85]
	v_pk_add_f32 v[56:57], v[56:57], v[70:71]
	v_pk_add_f32 v[58:59], v[58:59], v[72:73]
	s_waitcnt vmcnt(0)
	v_pk_add_f32 v[0:1], v[0:1], v[128:129]
	v_pk_add_f32 v[2:3], v[2:3], v[130:131]
	v_pk_add_f32 v[52:53], v[52:53], v[74:75]
	v_pk_add_f32 v[54:55], v[54:55], v[76:77]
	v_pk_add_f32 v[48:49], v[48:49], v[78:79]
	v_pk_add_f32 v[50:51], v[50:51], v[80:81]
	global_store_dwordx4 v[132:133], v[60:63], off
	global_store_dwordx4 v[132:133], v[56:59], off offset:64
	global_store_dwordx4 v[132:133], v[52:55], off offset:128
	global_store_dwordx4 v[132:133], v[48:51], off offset:192
	v_pk_add_f32 v[40:41], v[40:41], v[86:87]
	v_pk_add_f32 v[42:43], v[42:43], v[88:89]
	v_pk_add_f32 v[36:37], v[36:37], v[90:91]
	v_pk_add_f32 v[38:39], v[38:39], v[92:93]
	v_pk_add_f32 v[32:33], v[32:33], v[94:95]
	v_pk_add_f32 v[34:35], v[34:35], v[96:97]
	v_pk_add_f32 v[28:29], v[28:29], v[100:101]
	v_pk_add_f32 v[30:31], v[30:31], v[102:103]
	v_pk_add_f32 v[24:25], v[24:25], v[104:105]
	v_pk_add_f32 v[26:27], v[26:27], v[106:107]
	v_pk_add_f32 v[20:21], v[20:21], v[108:109]
	v_pk_add_f32 v[22:23], v[22:23], v[110:111]
	v_pk_add_f32 v[16:17], v[16:17], v[112:113]
	v_pk_add_f32 v[18:19], v[18:19], v[114:115]
	v_pk_add_f32 v[12:13], v[12:13], v[116:117]
	v_pk_add_f32 v[14:15], v[14:15], v[118:119]
	v_pk_add_f32 v[8:9], v[8:9], v[120:121]
	v_pk_add_f32 v[10:11], v[10:11], v[122:123]
	v_pk_add_f32 v[4:5], v[4:5], v[124:125]
	v_pk_add_f32 v[6:7], v[6:7], v[126:127]
	global_store_dwordx4 v[134:135], v[44:47], off
	global_store_dwordx4 v[134:135], v[40:43], off offset:64
	global_store_dwordx4 v[134:135], v[36:39], off offset:128
	global_store_dwordx4 v[134:135], v[32:35], off offset:192
	global_store_dwordx4 v[136:137], v[28:31], off
	global_store_dwordx4 v[136:137], v[24:27], off offset:64
	global_store_dwordx4 v[136:137], v[20:23], off offset:128
	global_store_dwordx4 v[136:137], v[16:19], off offset:192
	global_store_dwordx4 v[138:139], v[12:15], off
	global_store_dwordx4 v[138:139], v[8:11], off offset:64
	global_store_dwordx4 v[138:139], v[4:7], off offset:128
	global_store_dwordx4 v[138:139], v[0:3], off offset:192
	s_cbranch_scc1 .LBB0_1938

.LBB0_1990:
	s_or_b64 exec, exec, s[0:1]
	s_setprio 0
	s_waitcnt lgkmcnt(0)
	v_mov_b32_e32 v0, v174
	s_barrier
	v_readlane_b32 s0, v254, 55
	v_ashrrev_i32_e32 v1, 6, v174
	s_movk_i32 s7, 0x4400
	s_waitcnt vmcnt(10)
	v_add_u32_e32 v8, s0, v1
	v_cmp_gt_i32_e32 vcc, s7, v8
	s_and_saveexec_b64 s[0:1], vcc
	s_cbranch_execz .LBB0_2001
	v_mbcnt_hi_u32_b32 v1, -1, v175
	v_and_b32_e32 v3, 64, v1
	v_xor_b32_e32 v2, 16, v1
	v_add_u32_e32 v3, 64, v3
	v_cmp_lt_i32_e32 vcc, v2, v3
	v_lshlrev_b32_e32 v0, 2, v0
	v_and_b32_e32 v0, 0xfc, v0
	v_cndmask_b32_e32 v2, v1, v2, vcc
	v_lshlrev_b32_e32 v49, 2, v2
	v_xor_b32_e32 v2, 32, v1
	v_readlane_b32 s12, v254, 3
	v_cmp_lt_i32_e32 vcc, v2, v3
	v_mov_b32_e32 v45, 0
	v_lshlrev_b32_e32 v44, 2, v0
	v_readlane_b32 s24, v254, 15
	v_readlane_b32 s25, v254, 16
	v_cndmask_b32_e32 v1, v1, v2, vcc
	s_lshl_b32 s8, s28, 2
	v_lshl_add_u64 v[46:47], s[24:25], 0, v[44:45]
	v_lshlrev_b32_e32 v60, 2, v1
	s_mov_b64 s[4:5], 0
	s_movk_i32 s9, 0x43ff
	v_lshlrev_b32_e32 v44, 2, v0
	s_mov_b32 s6, 0x3a800000
	v_mov_b32_e32 v48, 0x358637bd
	s_mov_b32 s10, 0x800000
	v_readlane_b32 s13, v254, 4
	v_readlane_b32 s14, v254, 5
	v_readlane_b32 s15, v254, 6
	v_readlane_b32 s16, v254, 7
	v_readlane_b32 s17, v254, 8
	v_readlane_b32 s18, v254, 9
	v_readlane_b32 s19, v254, 10
	v_readlane_b32 s20, v254, 11
	v_readlane_b32 s21, v254, 12
	v_readlane_b32 s22, v254, 13
	v_readlane_b32 s23, v254, 14
	v_readlane_b32 s26, v254, 17
	v_readlane_b32 s27, v254, 18
	s_branch .LBB0_1993
